# all s_setprio flips in the GEMM loops deleted (A/B: faster); p->bf16 conversion moved from P5 into P4 mixer workgroups, scan records/u relocated +8 MiB in d_ws
# speedup vs baseline: 1.0492x; 1.0064x over previous
.LBB0_98:
	s_add_u32 s41, s48, 0xfffc0080
	s_addc_u32 s47, s49, -1
	s_add_i32 s54, 0, 0x10000
	s_cmp_eq_u32 s37, 12
	s_cselect_b32 s53, s30, s47
	s_cselect_b32 s52, s31, s41
	v_add_u32_e32 v143, s54, v140
	s_cselect_b32 s51, s19, s36
	s_cselect_b32 s50, s34, s35
	s_add_i32 s41, 0, 0x14000
	ds_read_b128 v[144:147], v143
	ds_read_b128 v[148:151], v143 offset:1024
	ds_read_b128 v[152:155], v143 offset:2048
	ds_read_b128 v[156:159], v143 offset:3072
	v_add_u32_e32 v143, s41, v140
	ds_read_b128 v[164:167], v143
	ds_read_b128 v[168:171], v143 offset:1024
	ds_read_b128 v[172:175], v143 offset:2048
	ds_read_b128 v[176:179], v143 offset:3072
	v_lshl_add_u64 v[204:205], s[48:49], 0, v[134:135]
	s_add_i32 m0, s22, 0xc000
	ds_read_b128 v[180:183], v142
	ds_read_b128 v[184:187], v142 offset:1024
	ds_read_b128 v[188:191], v142 offset:2048
	ds_read_b128 v[192:195], v142 offset:3072
	ds_read_b128 v[212:215], v142 offset:4096
	ds_read_b128 v[216:219], v142 offset:5120
	ds_read_b128 v[220:223], v142 offset:6144
	ds_read_b128 v[232:235], v142 offset:7168
	global_load_lds_dwordx4 v[204:205], off
	v_lshl_add_u64 v[204:205], s[48:49], 0, v[136:137]
	s_add_i32 m0, s22, 0xe000
	s_nop 0
	global_load_lds_dwordx4 v[204:205], off
	s_waitcnt vmcnt(8)
	s_waitcnt lgkmcnt(0)
	s_barrier
	s_waitcnt lgkmcnt(0)
	v_mfma_f32_16x16x32_bf16 v[124:127], v[144:147], v[180:183], v[124:127]
	v_mfma_f32_16x16x32_bf16 v[120:123], v[152:155], v[180:183], v[120:123]
	v_mfma_f32_16x16x32_bf16 v[116:119], v[144:147], v[188:191], v[116:119]
	v_mfma_f32_16x16x32_bf16 v[108:111], v[152:155], v[188:191], v[108:111]
	v_mfma_f32_16x16x32_bf16 v[100:103], v[144:147], v[212:215], v[100:103]
	v_mfma_f32_16x16x32_bf16 v[92:95], v[152:155], v[212:215], v[92:95]
	v_mfma_f32_16x16x32_bf16 v[84:87], v[144:147], v[220:223], v[84:87]
	v_mfma_f32_16x16x32_bf16 v[76:79], v[152:155], v[220:223], v[76:79]
	v_mfma_f32_16x16x32_bf16 v[124:127], v[148:151], v[184:187], v[124:127]
	v_mfma_f32_16x16x32_bf16 v[120:123], v[156:159], v[184:187], v[120:123]
	v_mfma_f32_16x16x32_bf16 v[116:119], v[148:151], v[192:195], v[116:119]
	v_mfma_f32_16x16x32_bf16 v[108:111], v[156:159], v[192:195], v[108:111]
	v_mfma_f32_16x16x32_bf16 v[100:103], v[148:151], v[216:219], v[100:103]
	v_mfma_f32_16x16x32_bf16 v[92:95], v[156:159], v[216:219], v[92:95]
	v_mfma_f32_16x16x32_bf16 v[84:87], v[148:151], v[232:235], v[84:87]
	v_mfma_f32_16x16x32_bf16 v[76:79], v[156:159], v[232:235], v[76:79]
	v_mfma_f32_16x16x32_bf16 v[112:115], v[164:167], v[180:183], v[112:115]
	v_mfma_f32_16x16x32_bf16 v[104:107], v[172:175], v[180:183], v[104:107]
	v_mfma_f32_16x16x32_bf16 v[96:99], v[164:167], v[188:191], v[96:99]
	v_mfma_f32_16x16x32_bf16 v[88:91], v[172:175], v[188:191], v[88:91]
	v_mfma_f32_16x16x32_bf16 v[80:83], v[164:167], v[212:215], v[80:83]
	v_mfma_f32_16x16x32_bf16 v[72:75], v[172:175], v[212:215], v[72:75]
	v_mfma_f32_16x16x32_bf16 v[68:71], v[164:167], v[220:223], v[68:71]
	v_mfma_f32_16x16x32_bf16 v[64:67], v[172:175], v[220:223], v[64:67]
	v_mfma_f32_16x16x32_bf16 v[112:115], v[168:171], v[184:187], v[112:115]
	v_mfma_f32_16x16x32_bf16 v[104:107], v[176:179], v[184:187], v[104:107]
	v_mfma_f32_16x16x32_bf16 v[96:99], v[168:171], v[192:195], v[96:99]
	v_mfma_f32_16x16x32_bf16 v[88:91], v[176:179], v[192:195], v[88:91]
	v_mfma_f32_16x16x32_bf16 v[80:83], v[168:171], v[216:219], v[80:83]
	v_mfma_f32_16x16x32_bf16 v[72:75], v[176:179], v[216:219], v[72:75]
	v_mfma_f32_16x16x32_bf16 v[68:71], v[168:171], v[232:235], v[68:71]
	v_mfma_f32_16x16x32_bf16 v[64:67], v[176:179], v[232:235], v[64:67]
	s_barrier
	s_add_i32 s47, s54, s20
	v_lshl_add_u64 v[204:205], s[50:51], 0, v[196:197]
	s_mov_b32 m0, s47
	ds_read_b128 v[180:183], v142 offset:16384
	ds_read_b128 v[184:187], v142 offset:17408
	ds_read_b128 v[188:191], v142 offset:18432
	ds_read_b128 v[192:195], v142 offset:19456
	ds_read_b128 v[212:215], v142 offset:20480
	ds_read_b128 v[216:219], v142 offset:21504
	ds_read_b128 v[220:223], v142 offset:22528
	ds_read_b128 v[232:235], v142 offset:23552
	global_load_lds_dwordx4 v[204:205], off
	s_add_i32 m0, s47, 0x2000
	s_add_u32 s54, s50, 0x40000
	v_lshl_add_u64 v[206:207], s[50:51], 0, v[128:129]
	s_addc_u32 s55, s51, 0
	s_add_i32 s41, s41, s20
	global_load_lds_dwordx4 v[206:207], off
	v_lshl_add_u64 v[236:237], s[54:55], 0, v[196:197]
	s_mov_b32 m0, s41
	v_lshl_add_u64 v[238:239], s[52:53], 0, v[130:131]
	global_load_lds_dwordx4 v[236:237], off
	v_lshl_add_u64 v[236:237], s[54:55], 0, v[128:129]
	s_add_i32 m0, s41, 0x2000
	s_nop 0
	global_load_lds_dwordx4 v[236:237], off
	v_lshl_add_u64 v[236:237], s[52:53], 0, v[132:133]
	s_mov_b32 m0, s22
	s_nop 0
	global_load_lds_dwordx4 v[236:237], off
	s_mov_b32 m0, s23
	s_nop 0
	global_load_lds_dwordx4 v[238:239], off
	s_waitcnt vmcnt(8)
	s_waitcnt lgkmcnt(0)
	s_barrier
	s_waitcnt lgkmcnt(0)
	v_mfma_f32_16x16x32_bf16 v[60:63], v[144:147], v[180:183], v[60:63]
	v_mfma_f32_16x16x32_bf16 v[56:59], v[152:155], v[180:183], v[56:59]
	v_mfma_f32_16x16x32_bf16 v[52:55], v[144:147], v[188:191], v[52:55]
	v_mfma_f32_16x16x32_bf16 v[44:47], v[152:155], v[188:191], v[44:47]
	v_mfma_f32_16x16x32_bf16 v[36:39], v[144:147], v[212:215], v[36:39]
	v_mfma_f32_16x16x32_bf16 v[28:31], v[152:155], v[212:215], v[28:31]
	v_mfma_f32_16x16x32_bf16 v[20:23], v[144:147], v[220:223], v[20:23]
	v_mfma_f32_16x16x32_bf16 v[12:15], v[152:155], v[220:223], v[12:15]
	v_mfma_f32_16x16x32_bf16 v[60:63], v[148:151], v[184:187], v[60:63]
	v_mfma_f32_16x16x32_bf16 v[56:59], v[156:159], v[184:187], v[56:59]
	v_mfma_f32_16x16x32_bf16 v[52:55], v[148:151], v[192:195], v[52:55]
	v_mfma_f32_16x16x32_bf16 v[44:47], v[156:159], v[192:195], v[44:47]
	v_mfma_f32_16x16x32_bf16 v[36:39], v[148:151], v[216:219], v[36:39]
	v_mfma_f32_16x16x32_bf16 v[28:31], v[156:159], v[216:219], v[28:31]
	v_mfma_f32_16x16x32_bf16 v[20:23], v[148:151], v[232:235], v[20:23]
	v_mfma_f32_16x16x32_bf16 v[12:15], v[156:159], v[232:235], v[12:15]
	v_mfma_f32_16x16x32_bf16 v[48:51], v[164:167], v[180:183], v[48:51]
	v_mfma_f32_16x16x32_bf16 v[40:43], v[172:175], v[180:183], v[40:43]
	v_mfma_f32_16x16x32_bf16 v[32:35], v[164:167], v[188:191], v[32:35]
	v_mfma_f32_16x16x32_bf16 v[24:27], v[172:175], v[188:191], v[24:27]
	v_mfma_f32_16x16x32_bf16 v[16:19], v[164:167], v[212:215], v[16:19]
	v_mfma_f32_16x16x32_bf16 v[8:11], v[172:175], v[212:215], v[8:11]
	v_mfma_f32_16x16x32_bf16 v[4:7], v[164:167], v[220:223], v[4:7]
	v_mfma_f32_16x16x32_bf16 v[0:3], v[172:175], v[220:223], v[0:3]
	v_mfma_f32_16x16x32_bf16 v[48:51], v[168:171], v[184:187], v[48:51]
	v_mfma_f32_16x16x32_bf16 v[40:43], v[176:179], v[184:187], v[40:43]
	v_mfma_f32_16x16x32_bf16 v[32:35], v[168:171], v[192:195], v[32:35]
	v_mfma_f32_16x16x32_bf16 v[24:27], v[176:179], v[192:195], v[24:27]
	v_mfma_f32_16x16x32_bf16 v[16:19], v[168:171], v[216:219], v[16:19]
	v_mfma_f32_16x16x32_bf16 v[8:11], v[176:179], v[216:219], v[8:11]
	v_mfma_f32_16x16x32_bf16 v[4:7], v[168:171], v[232:235], v[4:7]
	v_mfma_f32_16x16x32_bf16 v[0:3], v[176:179], v[232:235], v[0:3]
	s_barrier
	s_add_i32 s41, 0, 0x18000
	v_add_u32_e32 v143, s41, v140
	s_add_i32 s47, 0, 0x1c000
	ds_read_b128 v[144:147], v143
	ds_read_b128 v[148:151], v143 offset:1024
	ds_read_b128 v[152:155], v143 offset:2048
	ds_read_b128 v[156:159], v143 offset:3072
	v_add_u32_e32 v143, s47, v140
	ds_read_b128 v[164:167], v143
	ds_read_b128 v[168:171], v143 offset:1024
	ds_read_b128 v[172:175], v143 offset:2048
	ds_read_b128 v[176:179], v143 offset:3072
	s_add_u32 s52, s52, 0x40000
	s_addc_u32 s53, s53, 0
	s_mov_b32 m0, s24
	v_lshl_add_u64 v[240:241], s[52:53], 0, v[132:133]
	ds_read_b128 v[180:183], v142 offset:32768
	ds_read_b128 v[184:187], v142 offset:33792
	ds_read_b128 v[188:191], v142 offset:34816
	ds_read_b128 v[192:195], v142 offset:35840
	ds_read_b128 v[212:215], v142 offset:36864
	ds_read_b128 v[216:219], v142 offset:37888
	ds_read_b128 v[220:223], v142 offset:38912
	ds_read_b128 v[232:235], v142 offset:39936
	global_load_lds_dwordx4 v[240:241], off
	v_lshl_add_u64 v[240:241], s[52:53], 0, v[130:131]
	s_mov_b32 m0, s25
	s_nop 0
	global_load_lds_dwordx4 v[240:241], off
	s_waitcnt vmcnt(8)
	s_waitcnt lgkmcnt(0)
	s_barrier
	s_waitcnt lgkmcnt(0)
	v_mfma_f32_16x16x32_bf16 v[124:127], v[144:147], v[180:183], v[124:127]
	v_mfma_f32_16x16x32_bf16 v[120:123], v[152:155], v[180:183], v[120:123]
	v_mfma_f32_16x16x32_bf16 v[116:119], v[144:147], v[188:191], v[116:119]
	v_mfma_f32_16x16x32_bf16 v[108:111], v[152:155], v[188:191], v[108:111]
	v_mfma_f32_16x16x32_bf16 v[100:103], v[144:147], v[212:215], v[100:103]
	v_mfma_f32_16x16x32_bf16 v[92:95], v[152:155], v[212:215], v[92:95]
	v_mfma_f32_16x16x32_bf16 v[84:87], v[144:147], v[220:223], v[84:87]
	v_mfma_f32_16x16x32_bf16 v[76:79], v[152:155], v[220:223], v[76:79]
	v_mfma_f32_16x16x32_bf16 v[124:127], v[148:151], v[184:187], v[124:127]
	v_mfma_f32_16x16x32_bf16 v[120:123], v[156:159], v[184:187], v[120:123]
	v_mfma_f32_16x16x32_bf16 v[116:119], v[148:151], v[192:195], v[116:119]
	v_mfma_f32_16x16x32_bf16 v[108:111], v[156:159], v[192:195], v[108:111]
	v_mfma_f32_16x16x32_bf16 v[100:103], v[148:151], v[216:219], v[100:103]
	v_mfma_f32_16x16x32_bf16 v[92:95], v[156:159], v[216:219], v[92:95]
	v_mfma_f32_16x16x32_bf16 v[84:87], v[148:151], v[232:235], v[84:87]
	v_mfma_f32_16x16x32_bf16 v[76:79], v[156:159], v[232:235], v[76:79]
	v_mfma_f32_16x16x32_bf16 v[112:115], v[164:167], v[180:183], v[112:115]
	v_mfma_f32_16x16x32_bf16 v[104:107], v[172:175], v[180:183], v[104:107]
	v_mfma_f32_16x16x32_bf16 v[96:99], v[164:167], v[188:191], v[96:99]
	v_mfma_f32_16x16x32_bf16 v[88:91], v[172:175], v[188:191], v[88:91]
	v_mfma_f32_16x16x32_bf16 v[80:83], v[164:167], v[212:215], v[80:83]
	v_mfma_f32_16x16x32_bf16 v[72:75], v[172:175], v[212:215], v[72:75]
	v_mfma_f32_16x16x32_bf16 v[68:71], v[164:167], v[220:223], v[68:71]
	v_mfma_f32_16x16x32_bf16 v[64:67], v[172:175], v[220:223], v[64:67]
	v_mfma_f32_16x16x32_bf16 v[112:115], v[168:171], v[184:187], v[112:115]
	v_mfma_f32_16x16x32_bf16 v[104:107], v[176:179], v[184:187], v[104:107]
	v_mfma_f32_16x16x32_bf16 v[96:99], v[168:171], v[192:195], v[96:99]
	v_mfma_f32_16x16x32_bf16 v[88:91], v[176:179], v[192:195], v[88:91]
	v_mfma_f32_16x16x32_bf16 v[80:83], v[168:171], v[216:219], v[80:83]
	v_mfma_f32_16x16x32_bf16 v[72:75], v[176:179], v[216:219], v[72:75]
	v_mfma_f32_16x16x32_bf16 v[68:71], v[168:171], v[232:235], v[68:71]
	v_mfma_f32_16x16x32_bf16 v[64:67], v[176:179], v[232:235], v[64:67]
	s_barrier
	s_add_i32 s41, s41, s20
	v_lshl_add_u64 v[204:205], v[204:205], 0, s[10:11]
	s_mov_b32 m0, s41
	ds_read_b128 v[180:183], v142 offset:49152
	ds_read_b128 v[184:187], v142 offset:50176
	ds_read_b128 v[188:191], v142 offset:51200
	ds_read_b128 v[192:195], v142 offset:52224
	ds_read_b128 v[212:215], v142 offset:53248
	ds_read_b128 v[216:219], v142 offset:54272
	ds_read_b128 v[220:223], v142 offset:55296
	ds_read_b128 v[232:235], v142 offset:56320
	global_load_lds_dwordx4 v[204:205], off
	s_add_i32 m0, s41, 0x2000
	s_add_u32 s50, s50, 0x40080
	v_lshl_add_u64 v[204:205], v[206:207], 0, s[10:11]
	s_addc_u32 s51, s51, 0
	s_add_i32 s41, s47, s20
	global_load_lds_dwordx4 v[204:205], off
	v_lshl_add_u64 v[204:205], s[50:51], 0, v[196:197]
	s_mov_b32 m0, s41
	s_nop 0
	global_load_lds_dwordx4 v[204:205], off
	v_lshl_add_u64 v[204:205], s[50:51], 0, v[128:129]
	s_add_i32 m0, s41, 0x2000
	s_nop 0
	global_load_lds_dwordx4 v[204:205], off
	v_lshl_add_u64 v[204:205], v[236:237], 0, s[10:11]
	s_mov_b32 m0, s26
	s_nop 0
	global_load_lds_dwordx4 v[204:205], off
	v_lshl_add_u64 v[204:205], v[238:239], 0, s[10:11]
	s_mov_b32 m0, s27
	s_nop 0
	global_load_lds_dwordx4 v[204:205], off
	s_waitcnt vmcnt(8)
	s_waitcnt lgkmcnt(0)
	s_barrier
	s_waitcnt lgkmcnt(0)
	v_mfma_f32_16x16x32_bf16 v[60:63], v[144:147], v[180:183], v[60:63]
	v_mfma_f32_16x16x32_bf16 v[56:59], v[152:155], v[180:183], v[56:59]
	v_mfma_f32_16x16x32_bf16 v[52:55], v[144:147], v[188:191], v[52:55]
	v_mfma_f32_16x16x32_bf16 v[44:47], v[152:155], v[188:191], v[44:47]
	v_mfma_f32_16x16x32_bf16 v[36:39], v[144:147], v[212:215], v[36:39]
	v_mfma_f32_16x16x32_bf16 v[28:31], v[152:155], v[212:215], v[28:31]
	v_mfma_f32_16x16x32_bf16 v[20:23], v[144:147], v[220:223], v[20:23]
	v_mfma_f32_16x16x32_bf16 v[12:15], v[152:155], v[220:223], v[12:15]
	v_mfma_f32_16x16x32_bf16 v[60:63], v[148:151], v[184:187], v[60:63]
	v_mfma_f32_16x16x32_bf16 v[56:59], v[156:159], v[184:187], v[56:59]
	v_mfma_f32_16x16x32_bf16 v[52:55], v[148:151], v[192:195], v[52:55]
	v_mfma_f32_16x16x32_bf16 v[44:47], v[156:159], v[192:195], v[44:47]
	v_mfma_f32_16x16x32_bf16 v[36:39], v[148:151], v[216:219], v[36:39]
	v_mfma_f32_16x16x32_bf16 v[28:31], v[156:159], v[216:219], v[28:31]
	v_mfma_f32_16x16x32_bf16 v[20:23], v[148:151], v[232:235], v[20:23]
	v_mfma_f32_16x16x32_bf16 v[12:15], v[156:159], v[232:235], v[12:15]
	v_mfma_f32_16x16x32_bf16 v[48:51], v[164:167], v[180:183], v[48:51]
	v_mfma_f32_16x16x32_bf16 v[40:43], v[172:175], v[180:183], v[40:43]
	v_mfma_f32_16x16x32_bf16 v[32:35], v[164:167], v[188:191], v[32:35]
	v_mfma_f32_16x16x32_bf16 v[24:27], v[172:175], v[188:191], v[24:27]
	v_mfma_f32_16x16x32_bf16 v[16:19], v[164:167], v[212:215], v[16:19]
	v_mfma_f32_16x16x32_bf16 v[8:11], v[172:175], v[212:215], v[8:11]
	v_mfma_f32_16x16x32_bf16 v[4:7], v[164:167], v[220:223], v[4:7]
	v_mfma_f32_16x16x32_bf16 v[0:3], v[172:175], v[220:223], v[0:3]
	v_mfma_f32_16x16x32_bf16 v[48:51], v[168:171], v[184:187], v[48:51]
	v_mfma_f32_16x16x32_bf16 v[40:43], v[176:179], v[184:187], v[40:43]
	v_mfma_f32_16x16x32_bf16 v[32:35], v[168:171], v[192:195], v[32:35]
	v_mfma_f32_16x16x32_bf16 v[24:27], v[176:179], v[192:195], v[24:27]
	v_mfma_f32_16x16x32_bf16 v[16:19], v[168:171], v[216:219], v[16:19]
	v_mfma_f32_16x16x32_bf16 v[8:11], v[176:179], v[216:219], v[8:11]
	v_mfma_f32_16x16x32_bf16 v[4:7], v[168:171], v[232:235], v[4:7]
	v_mfma_f32_16x16x32_bf16 v[0:3], v[176:179], v[232:235], v[0:3]
	s_barrier
	s_add_i32 s37, s37, 2
	s_add_u32 s48, s48, 0x100
	s_addc_u32 s49, s49, 0
	s_add_u32 s35, s35, 0x100
	s_addc_u32 s36, s36, 0
	s_cmp_gt_u32 s37, 13
	s_cbranch_scc0 .LBB0_98
	s_and_b64 vcc, exec, s[16:17]
	s_cbranch_vccz .LBB0_101
	s_barrier

.LBB0_182:
	s_or_b64 exec, exec, s[6:7]
	v_mov_b32_e32 v35, v211
	s_mov_b32 s4, s74
	s_mov_b32 s80, s94
	s_mov_b32 s82, s75
	s_waitcnt lgkmcnt(0)
	s_barrier
	v_readlane_b32 s1, v255, 31
	v_readfirstlane_b32 s0, v35
	s_mov_b64 s[8:9], s[92:93]
	s_cmpk_lt_i32 s4, 0x100
	s_cbranch_scc0 .LBB0_318
	s_mul_i32 s2, s1, 0x1800
	s_ashr_i32 s3, s2, 31
	v_readlane_b32 s12, v254, 10
	s_lshl_b64 s[2:3], s[2:3], 2
	v_readlane_b32 s14, v254, 12
	v_readlane_b32 s20, v254, 18
	v_readlane_b32 s15, v254, 13
	v_readlane_b32 s21, v254, 19
	s_add_u32 s14, s20, s2
	v_readlane_b32 s16, v254, 14
	s_addc_u32 s15, s21, s3
	s_ashr_i32 s12, s0, 6
	v_readlane_b32 s17, v254, 15
	s_add_u32 s16, s8, 0x140000
	v_readlane_b32 s18, v254, 16
	s_addc_u32 s17, s9, 0
	v_readlane_b32 s19, v254, 17
	v_and_b32_e32 v34, 3, v35
	s_add_u32 s18, s8, 0x180000
	s_movk_i32 s1, 0x100
	v_ashrrev_i32_e32 v32, 2, v35
	v_lshlrev_b32_e32 v1, 6, v34
	s_addc_u32 s19, s9, 0
	v_cmp_gt_i32_e64 s[38:39], s1, v35
	v_add_lshl_u32 v1, v1, v32, 2
	v_readlane_b32 s1, v255, 25
	s_cmp_lt_i32 s12, 4
	s_cselect_b64 s[60:61], -1, 0
	v_add_u32_e32 v39, s1, v1
	s_and_b32 s1, s0, 0xffffffc0
	s_add_u32 s81, s8, 0xa600000
	v_readlane_b32 s3, v255, 24
	s_addc_u32 s75, s9, 0
	v_readlane_b32 s13, v254, 11
	v_add_u32_e32 v38, s3, v1
	v_mov_b32_e32 v1, s0
	s_movk_i32 s2, 0xffc0
	s_add_u32 s62, s8, 0x3e00000
	v_bfi_b32 v1, s2, v1, v35
	s_addc_u32 s63, s9, 0
	s_and_b32 s13, s12, 1
	v_lshlrev_b32_e32 v1, 2, v1
	s_bitcmp1_b32 s0, 7
	v_add_u32_e32 v40, s3, v1
	s_cselect_b64 s[2:3], -1, 0
	s_cmp_eq_u32 s13, 0
	s_cselect_b64 s[6:7], -1, 0
	s_or_b64 s[64:65], s[2:3], s[6:7]
	s_cmpk_gt_u32 s0, 0xff
	s_cselect_b64 s[66:67], -1, 0
	s_lshr_b32 s2, s0, 2
	s_and_b32 s2, s2, 32
	s_lshl_b32 s36, s13, 5
	s_cmp_gt_i32 s12, 1
	s_mul_i32 s3, s12, 0x2200
	v_readlane_b32 s22, v254, 20
	s_cselect_b64 s[68:69], -1, 0
	s_lshl_b32 s6, s12, 7
	s_add_i32 s3, s3, 0
	s_add_i32 s21, s3, s6
	s_add_i32 s22, s1, 0
	s_lshl_b32 s37, s12, 5
	s_add_i32 s20, s21, 0x16000
	s_add_i32 s21, s21, 0x1d400
	s_add_i32 s22, s22, 0x1a400
	s_cmp_lt_u32 s0, 64
	s_cselect_b64 s[70:71], -1, 0
	s_cmpk_lt_u32 s0, 0x100
	s_cselect_b64 s[72:73], -1, 0
	s_and_b64 s[0:1], s[72:73], exec
	v_readlane_b32 s23, v254, 21
	v_readlane_b32 s0, v255, 26
	v_readlane_b32 s24, v254, 22
	v_readlane_b32 s25, v254, 23
	s_cselect_b32 s23, 0, s0
	v_readlane_b32 s0, v255, 27
	s_cselect_b32 s24, s0, s88
	s_and_b32 s25, s37, 0x60
	v_readlane_b32 s26, v254, 24
	s_add_u32 s6, s8, 0xe300000
	v_readlane_b32 s27, v254, 25
	s_addc_u32 s7, s9, 0
	s_lshl_b32 s26, s12, 1
	v_and_b32_e32 v0, 63, v35
	s_add_u32 s27, s8, 0x100000
	s_mulk_i32 s12, 0x1200
	v_ashrrev_i32_e32 v33, 31, v32
	v_add_u32_e32 v41, s84, v1
	s_addc_u32 s96, s9, 0
	v_cmp_eq_u32_e64 s[40:41], 0, v0
	v_cmp_gt_u32_e64 s[42:43], 2, v0
	v_cmp_gt_u32_e64 s[44:45], 4, v0
	v_cmp_gt_u32_e64 s[46:47], 8, v0
	v_cmp_gt_u32_e64 s[48:49], 16, v0
	v_cmp_gt_u32_e64 s[50:51], 32, v0
	s_xor_b32 s97, s25, 32
	s_xor_b32 s3, s25, 64
	s_xor_b32 s0, s25, 0x60
	s_add_i32 s1, s22, s12
	s_branch .LBB0_185

.LBB0_370:
	s_or_b64 exec, exec, s[6:7]
	v_mov_b32_e32 v212, v211
	s_waitcnt lgkmcnt(0)
	s_barrier
	s_mov_b32 s1, s94
	v_readfirstlane_b32 s2, v212
	s_ashr_i32 s16, s2, 6
	s_mov_b32 s0, s74
	v_bfe_u32 v199, v212, 5, 1
	v_readlane_b32 s3, v255, 31
	v_and_b32_e32 v231, 63, v212
	v_and_b32_e32 v210, 31, v212
	s_mov_b32 s18, s3
	s_mov_b64 s[14:15], s[92:93]
	s_cmp_gt_i32 s0, 31
	v_lshlrev_b32_e32 v232, 3, v199
	s_cbranch_scc1 .LBB0_514
	s_add_u32 s3, s14, 0xa600000
	s_addc_u32 s19, s15, 0
	s_cmp_lt_i32 s16, 4
	s_cselect_b64 s[6:7], -1, 0
	s_add_u32 s8, s14, 0x100000
	s_addc_u32 s9, s15, 0
	s_ashr_i32 s17, s16, 31
	s_lshl_b64 s[12:13], s[16:17], 12
	s_add_u32 s12, s14, s12
	s_addc_u32 s13, s15, s13
	v_lshlrev_b32_e32 v196, 4, v231
	v_lshl_add_u64 v[0:1], s[12:13], 0, v[196:197]
	s_mov_b64 s[12:13], 0xe300000
	v_lshl_add_u64 v[214:215], v[0:1], 0, s[12:13]
	v_lshlrev_b32_e32 v1, 4, v199
	v_lshlrev_b32_e32 v2, 1, v212
	v_bitop3_b32 v196, v1, v212, 16 bitop3:0x78
	v_and_b32_e32 v1, 1, v212
	v_and_b32_e32 v2, 60, v2
	s_movk_i32 s4, 0xf40
	s_add_u32 s17, s14, 0x3e00000
	v_cmp_eq_u32_e64 s[40:41], 0, v1
	v_lshl_or_b32 v1, v1, 10, v2
	v_cmp_gt_i32_e64 s[38:39], s4, v212
	s_addc_u32 s20, s15, 0
	s_and_b32 s4, s2, 0xffffffc0
	v_lshl_or_b32 v1, v199, 12, v1
	v_lshlrev_b32_e32 v233, 4, v212
	v_mul_u32_u24_e32 v0, 0x48, v210
	v_add_u32_e32 v213, s4, v1
	v_lshlrev_b32_e32 v1, 8, v212
	v_and_b32_e32 v2, 0xf0, v233
	s_movk_i32 s4, 0xf000
	v_and_or_b32 v1, v1, s4, v2
	v_lshlrev_b32_e32 v236, 1, v232
	v_lshlrev_b32_e32 v0, 1, v0
	v_readlane_b32 s4, v255, 28
	v_add_u32_e32 v216, 0xffff0000, v1
	v_ashrrev_i32_e32 v217, 31, v216
	v_add3_u32 v239, s4, v0, v236
	s_mov_b32 s4, 0xf400
	v_add_u32_e32 v0, 0xffff0100, v1
	v_cmp_gt_i32_e64 s[44:45], s4, v0
	v_add_u32_e32 v0, 0xffff0200, v1
	v_cmp_gt_i32_e64 s[46:47], s4, v0
	v_add_u32_e32 v0, 0xffff0300, v1
	v_cmp_gt_i32_e64 s[48:49], s4, v0
	v_add_u32_e32 v0, 0xffff0400, v1
	v_cmp_gt_i32_e64 s[50:51], s4, v0
	v_add_u32_e32 v0, 0xffff0500, v1
	v_cmp_gt_i32_e64 s[52:53], s4, v0
	v_add_u32_e32 v0, 0xffff0600, v1
	v_cmp_gt_i32_e64 s[54:55], s4, v0
	v_add_u32_e32 v0, 0xffff0700, v1
	v_cmp_gt_i32_e64 s[56:57], s4, v0
	v_add_u32_e32 v0, 0xffff0800, v1
	v_cmp_gt_i32_e64 s[58:59], s4, v0
	v_add_u32_e32 v0, 0xffff0900, v1
	v_cmp_gt_i32_e64 s[60:61], s4, v0
	v_add_u32_e32 v0, 0xffff0a00, v1
	v_cmp_gt_i32_e64 s[62:63], s4, v0
	v_add_u32_e32 v0, 0xffff0b00, v1
	v_cmp_gt_i32_e64 s[64:65], s4, v0
	v_add_u32_e32 v0, 0xffff0c00, v1
	v_cmp_gt_i32_e64 s[66:67], s4, v0
	v_add_u32_e32 v0, 0xffff0d00, v1
	v_cmp_gt_i32_e64 s[68:69], s4, v0
	v_add_u32_e32 v0, 0xffff0e00, v1
	v_cmp_gt_i32_e64 s[70:71], s4, v0
	v_add_u32_e32 v0, 0xffff0f00, v1
	v_mad_u32_u24 v235, v210, s87, 0
	v_cmp_gt_i32_e64 s[72:73], s4, v0
	v_lshlrev_b32_e32 v0, 7, v210
	v_add_u32_e32 v234, 0, v216
	v_add_u32_e32 v237, v235, v236
	v_sub_u32_e32 v244, 0, v0
	s_lshl_b32 s21, s0, 5
	v_lshl_add_u64 v[0:1], s[14:15], 0, v[216:217]
	s_mov_b64 s[12:13], 0xa63df00
	v_add_u32_e32 v238, 0xf400, v237
	v_cmp_gt_i32_e64 s[42:43], s4, v216
	v_add_u32_e32 v240, 0x10000, v234
	v_add_u32_e32 v241, 0x10100, v234
	v_add_u32_e32 v242, 0x10200, v234
	v_add_u32_e32 v243, 0x10300, v234
	v_add_u32_e32 v245, 0xfffffe00, v212
	s_or_b32 s22, s21, 1
	s_lshl_b32 s23, s1, 5
	s_lshl_b32 s24, s0, 7
	s_lshl_b32 s25, s1, 7
	v_lshl_add_u64 v[218:219], v[0:1], 0, s[12:13]
	s_mov_b32 s26, s0
	s_branch .LBB0_374

.LBB0_564:
	s_cmp_lt_u32 s74, 32
	s_cbranch_scc1 .Lp4_pc_done
	v_readlane_b32 s96, v254, 12
	v_readlane_b32 s97, v254, 13
	v_readlane_b32 s98, v255, 31
	s_nop 1
	s_lshl_b32 s98, s98, 24
	s_add_u32 s96, s96, s98
	s_addc_u32 s97, s97, 0
	s_sub_u32 s98, s74, 32
	s_lshl_b32 s98, s98, 9
	v_add_u32_e32 v0, s98, v211
	s_add_u32 s98, s92, 0x9e00000
	s_addc_u32 s99, s93, 0
	s_mov_b32 s0, 0
.Lp4_pc_loop:
	v_cmp_gt_u32_e32 vcc, 0x80000, v0
	s_and_saveexec_b64 s[2:3], vcc
	s_cbranch_execz .Lp4_pc_skip
	v_lshlrev_b32_e32 v1, 5, v0
	global_load_dwordx4 v[2:5], v1, s[96:97]
	global_load_dwordx4 v[6:9], v1, s[96:97] offset:16
	v_lshlrev_b32_e32 v1, 4, v0
	s_waitcnt vmcnt(0)
	v_cvt_pk_bf16_f32 v2, v2, v3
	v_cvt_pk_bf16_f32 v3, v4, v5
	v_cvt_pk_bf16_f32 v4, v6, v7
	v_cvt_pk_bf16_f32 v5, v8, v9
	global_store_dwordx4 v1, v[2:5], s[98:99]
.Lp4_pc_skip:
	s_or_b64 exec, exec, s[2:3]
	v_add_u32_e32 v0, 0x1c000, v0
	s_add_i32 s0, s0, 1
	s_cmp_lt_u32 s0, 5
	s_cbranch_scc1 .Lp4_pc_loop

.LBB0_630:
	s_ashr_i32 s13, s12, 31
	v_readlane_b32 s16, v254, 10
	s_lshl_b64 s[2:3], s[12:13], 24
	v_readlane_b32 s18, v254, 12
	v_readlane_b32 s17, v254, 11
	v_readlane_b32 s19, v254, 13
	s_add_u32 s16, s18, s2
	v_ashrrev_i32_e32 v1, 31, v0
	s_addc_u32 s17, s19, s3
	v_lshl_add_u64 v[2:3], v[0:1], 4, s[8:9]
	s_mov_b64 s[2:3], 0x9e00000
	s_ashr_i32 s7, s6, 31
	v_lshlrev_b32_e32 v1, 1, v10
	v_lshl_add_u64 v[2:3], v[2:3], 0, s[2:3]
	s_lshl_b64 s[18:19], s[6:7], 4
	v_lshl_add_u32 v4, s1, 10, v1
	s_lshl_b32 s2, s0, 10
	s_mov_b64 s[38:39], 0
	v_mov_b32_e32 v1, v0
	v_readlane_b32 s20, v254, 14
	v_readlane_b32 s21, v254, 15
	v_readlane_b32 s22, v254, 16
	v_readlane_b32 s23, v254, 17
	v_readlane_b32 s24, v254, 18
	v_readlane_b32 s25, v254, 19
	v_readlane_b32 s26, v254, 20
	v_readlane_b32 s27, v254, 21
	v_readlane_b32 s28, v254, 22
	v_readlane_b32 s29, v254, 23
	v_readlane_b32 s30, v254, 24
	v_readlane_b32 s31, v254, 25
	s_branch .Lp5_skip_p

.Lp5_skip_p:
	s_or_b64 exec, exec, s[38:39]
	s_lshl_b32 s2, s12, 7
	s_ashr_i32 s3, s2, 31
	v_readlane_b32 s16, v254, 10
	v_and_b32_e32 v2, 64, v227
	s_lshl_b64 s[2:3], s[2:3], 2
	v_readlane_b32 s30, v254, 24
	v_xor_b32_e32 v1, 1, v227
	v_add_u32_e32 v2, 64, v2
	v_readlane_b32 s31, v254, 25
	s_add_u32 s12, s30, s2
	v_cmp_lt_i32_e32 vcc, v1, v2
	v_xor_b32_e32 v3, 2, v227
	s_addc_u32 s13, s31, s3
	v_cndmask_b32_e32 v1, v227, v1, vcc
	v_cmp_lt_i32_e32 vcc, v3, v2
	v_readlane_b32 s17, v254, 11
	s_add_u32 s16, s8, 0x3e00000
	v_cndmask_b32_e32 v3, v227, v3, vcc
	v_readlane_b32 s18, v254, 12
	s_addc_u32 s17, s9, 0
	v_lshlrev_b32_e32 v8, 2, v3
	v_xor_b32_e32 v3, 4, v227
	v_readlane_b32 s19, v254, 13
	v_cmp_lt_i32_e32 vcc, v3, v2
	s_add_u32 s18, s8, 0x6e00000
	s_addc_u32 s19, s9, 0
	v_cndmask_b32_e32 v2, v227, v3, vcc
	v_lshlrev_b32_e32 v9, 2, v2
	s_add_u32 s8, s8, 0x1e00000
	v_lshlrev_b32_e32 v2, 4, v10
	v_lshlrev_b32_e32 v1, 2, v1
	s_addc_u32 s9, s9, 0
	v_lshl_add_u32 v10, s1, 13, v2
	s_lshl_b32 s0, s0, 13
	s_mov_b64 s[38:39], 0
	v_readlane_b32 s20, v254, 14
	v_readlane_b32 s21, v254, 15
	v_readlane_b32 s22, v254, 16
	v_readlane_b32 s23, v254, 17
	v_readlane_b32 s24, v254, 18
	v_readlane_b32 s25, v254, 19
	v_readlane_b32 s26, v254, 20
	v_readlane_b32 s27, v254, 21
	v_readlane_b32 s28, v254, 22
	v_readlane_b32 s29, v254, 23

.LBB0_701:
	s_add_u32 s48, s14, s46
	s_addc_u32 s49, s15, s47
	s_add_u32 s48, s48, 0x100
	s_addc_u32 s49, s49, 0
	s_add_u32 s55, s36, s46
	s_addc_u32 s56, s37, s47
	s_add_i32 s57, 0, 0x10000
	s_cmpk_eq_i32 s46, 0x700
	s_cselect_b32 s51, s19, s49
	s_cselect_b32 s50, s52, s48
	v_add_u32_e32 v147, s57, v144
	s_cselect_b32 s49, s17, s56
	s_cselect_b32 s48, s53, s55
	s_add_i32 s55, 0, 0x14000
	ds_read_b128 v[148:151], v147
	ds_read_b128 v[152:155], v147 offset:1024
	ds_read_b128 v[156:159], v147 offset:2048
	ds_read_b128 v[164:167], v147 offset:3072
	v_add_u32_e32 v147, s55, v144
	ds_read_b128 v[168:171], v147
	ds_read_b128 v[172:175], v147 offset:1024
	ds_read_b128 v[176:179], v147 offset:2048
	ds_read_b128 v[180:183], v147 offset:3072
	v_lshl_add_u64 v[236:237], v[138:139], 0, s[46:47]
	s_add_i32 m0, s9, 0xc000
	ds_read_b128 v[184:187], v145
	ds_read_b128 v[188:191], v145 offset:1024
	ds_read_b128 v[192:195], v145 offset:2048
	ds_read_b128 v[204:207], v145 offset:3072
	ds_read_b128 v[212:215], v145 offset:4096
	ds_read_b128 v[216:219], v145 offset:5120
	ds_read_b128 v[220:223], v145 offset:6144
	ds_read_b128 v[232:235], v145 offset:7168
	global_load_lds_dwordx4 v[236:237], off
	v_lshl_add_u64 v[236:237], v[140:141], 0, s[46:47]
	s_add_i32 m0, s9, 0xe000
	s_nop 0
	global_load_lds_dwordx4 v[236:237], off
	s_waitcnt vmcnt(8)
	s_waitcnt lgkmcnt(0)
	s_barrier
	s_waitcnt lgkmcnt(0)
	v_mfma_f32_16x16x32_bf16 v[68:71], v[148:151], v[184:187], v[68:71]
	v_mfma_f32_16x16x32_bf16 v[64:67], v[156:159], v[184:187], v[64:67]
	v_mfma_f32_16x16x32_bf16 v[112:115], v[148:151], v[192:195], v[112:115]
	v_mfma_f32_16x16x32_bf16 v[108:111], v[156:159], v[192:195], v[108:111]
	v_mfma_f32_16x16x32_bf16 v[76:79], v[148:151], v[212:215], v[76:79]
	v_mfma_f32_16x16x32_bf16 v[72:75], v[156:159], v[212:215], v[72:75]
	v_mfma_f32_16x16x32_bf16 v[92:95], v[148:151], v[220:223], v[92:95]
	v_mfma_f32_16x16x32_bf16 v[88:91], v[156:159], v[220:223], v[88:91]
	v_mfma_f32_16x16x32_bf16 v[68:71], v[152:155], v[188:191], v[68:71]
	v_mfma_f32_16x16x32_bf16 v[64:67], v[164:167], v[188:191], v[64:67]
	v_mfma_f32_16x16x32_bf16 v[112:115], v[152:155], v[204:207], v[112:115]
	v_mfma_f32_16x16x32_bf16 v[108:111], v[164:167], v[204:207], v[108:111]
	v_mfma_f32_16x16x32_bf16 v[76:79], v[152:155], v[216:219], v[76:79]
	v_mfma_f32_16x16x32_bf16 v[72:75], v[164:167], v[216:219], v[72:75]
	v_mfma_f32_16x16x32_bf16 v[92:95], v[152:155], v[232:235], v[92:95]
	v_mfma_f32_16x16x32_bf16 v[88:91], v[164:167], v[232:235], v[88:91]
	v_mfma_f32_16x16x32_bf16 v[96:99], v[168:171], v[184:187], v[96:99]
	v_mfma_f32_16x16x32_bf16 v[100:103], v[176:179], v[184:187], v[100:103]
	v_mfma_f32_16x16x32_bf16 v[120:123], v[168:171], v[192:195], v[120:123]
	v_mfma_f32_16x16x32_bf16 v[124:127], v[176:179], v[192:195], v[124:127]
	v_mfma_f32_16x16x32_bf16 v[84:87], v[168:171], v[212:215], v[84:87]
	v_mfma_f32_16x16x32_bf16 v[80:83], v[176:179], v[212:215], v[80:83]
	v_mfma_f32_16x16x32_bf16 v[116:119], v[168:171], v[220:223], v[116:119]
	v_mfma_f32_16x16x32_bf16 v[104:107], v[176:179], v[220:223], v[104:107]
	v_mfma_f32_16x16x32_bf16 v[96:99], v[172:175], v[188:191], v[96:99]
	v_mfma_f32_16x16x32_bf16 v[100:103], v[180:183], v[188:191], v[100:103]
	v_mfma_f32_16x16x32_bf16 v[120:123], v[172:175], v[204:207], v[120:123]
	v_mfma_f32_16x16x32_bf16 v[124:127], v[180:183], v[204:207], v[124:127]
	v_mfma_f32_16x16x32_bf16 v[84:87], v[172:175], v[216:219], v[84:87]
	v_mfma_f32_16x16x32_bf16 v[80:83], v[180:183], v[216:219], v[80:83]
	v_mfma_f32_16x16x32_bf16 v[116:119], v[172:175], v[232:235], v[116:119]
	v_mfma_f32_16x16x32_bf16 v[104:107], v[180:183], v[232:235], v[104:107]
	s_barrier
	s_add_i32 s56, s57, s25
	v_lshl_add_u64 v[236:237], s[48:49], 0, v[196:197]
	s_mov_b32 m0, s56
	ds_read_b128 v[184:187], v145 offset:16384
	ds_read_b128 v[188:191], v145 offset:17408
	ds_read_b128 v[192:195], v145 offset:18432
	ds_read_b128 v[204:207], v145 offset:19456
	ds_read_b128 v[212:215], v145 offset:20480
	ds_read_b128 v[216:219], v145 offset:21504
	ds_read_b128 v[220:223], v145 offset:22528
	ds_read_b128 v[232:235], v145 offset:23552
	global_load_lds_dwordx4 v[236:237], off
	s_add_i32 m0, s56, 0x2000
	s_add_u32 s56, s48, 0x40000
	v_lshl_add_u64 v[238:239], s[48:49], 0, v[132:133]
	s_addc_u32 s57, s49, 0
	s_add_i32 s55, s55, s25
	global_load_lds_dwordx4 v[238:239], off
	v_lshl_add_u64 v[240:241], s[56:57], 0, v[196:197]
	s_mov_b32 m0, s55
	v_lshl_add_u64 v[242:243], s[50:51], 0, v[130:131]
	global_load_lds_dwordx4 v[240:241], off
	v_lshl_add_u64 v[240:241], s[56:57], 0, v[132:133]
	s_add_i32 m0, s55, 0x2000
	s_nop 0
	global_load_lds_dwordx4 v[240:241], off
	v_lshl_add_u64 v[240:241], s[50:51], 0, v[128:129]
	s_mov_b32 m0, s9
	s_nop 0
	global_load_lds_dwordx4 v[240:241], off
	s_mov_b32 m0, s27
	s_nop 0
	global_load_lds_dwordx4 v[242:243], off
	s_waitcnt vmcnt(8)
	s_waitcnt lgkmcnt(0)
	s_barrier
	s_waitcnt lgkmcnt(0)
	v_mfma_f32_16x16x32_bf16 v[60:63], v[148:151], v[184:187], v[60:63]
	v_mfma_f32_16x16x32_bf16 v[56:59], v[156:159], v[184:187], v[56:59]
	v_mfma_f32_16x16x32_bf16 v[44:47], v[148:151], v[192:195], v[44:47]
	v_mfma_f32_16x16x32_bf16 v[40:43], v[156:159], v[192:195], v[40:43]
	v_mfma_f32_16x16x32_bf16 v[28:31], v[148:151], v[212:215], v[28:31]
	v_mfma_f32_16x16x32_bf16 v[24:27], v[156:159], v[212:215], v[24:27]
	v_mfma_f32_16x16x32_bf16 v[12:15], v[148:151], v[220:223], v[12:15]
	v_mfma_f32_16x16x32_bf16 v[8:11], v[156:159], v[220:223], v[8:11]
	v_mfma_f32_16x16x32_bf16 v[60:63], v[152:155], v[188:191], v[60:63]
	v_mfma_f32_16x16x32_bf16 v[56:59], v[164:167], v[188:191], v[56:59]
	v_mfma_f32_16x16x32_bf16 v[44:47], v[152:155], v[204:207], v[44:47]
	v_mfma_f32_16x16x32_bf16 v[40:43], v[164:167], v[204:207], v[40:43]
	v_mfma_f32_16x16x32_bf16 v[28:31], v[152:155], v[216:219], v[28:31]
	v_mfma_f32_16x16x32_bf16 v[24:27], v[164:167], v[216:219], v[24:27]
	v_mfma_f32_16x16x32_bf16 v[12:15], v[152:155], v[232:235], v[12:15]
	v_mfma_f32_16x16x32_bf16 v[8:11], v[164:167], v[232:235], v[8:11]
	v_mfma_f32_16x16x32_bf16 v[52:55], v[168:171], v[184:187], v[52:55]
	v_mfma_f32_16x16x32_bf16 v[48:51], v[176:179], v[184:187], v[48:51]
	v_mfma_f32_16x16x32_bf16 v[36:39], v[168:171], v[192:195], v[36:39]
	v_mfma_f32_16x16x32_bf16 v[32:35], v[176:179], v[192:195], v[32:35]
	v_mfma_f32_16x16x32_bf16 v[20:23], v[168:171], v[212:215], v[20:23]
	v_mfma_f32_16x16x32_bf16 v[16:19], v[176:179], v[212:215], v[16:19]
	v_mfma_f32_16x16x32_bf16 v[4:7], v[168:171], v[220:223], v[4:7]
	v_mfma_f32_16x16x32_bf16 v[0:3], v[176:179], v[220:223], v[0:3]
	v_mfma_f32_16x16x32_bf16 v[52:55], v[172:175], v[188:191], v[52:55]
	v_mfma_f32_16x16x32_bf16 v[48:51], v[180:183], v[188:191], v[48:51]
	v_mfma_f32_16x16x32_bf16 v[36:39], v[172:175], v[204:207], v[36:39]
	v_mfma_f32_16x16x32_bf16 v[32:35], v[180:183], v[204:207], v[32:35]
	v_mfma_f32_16x16x32_bf16 v[20:23], v[172:175], v[216:219], v[20:23]
	v_mfma_f32_16x16x32_bf16 v[16:19], v[180:183], v[216:219], v[16:19]
	v_mfma_f32_16x16x32_bf16 v[4:7], v[172:175], v[232:235], v[4:7]
	v_mfma_f32_16x16x32_bf16 v[0:3], v[180:183], v[232:235], v[0:3]
	s_barrier
	s_add_i32 s55, 0, 0x18000
	v_add_u32_e32 v147, s55, v144
	s_add_i32 s56, 0, 0x1c000
	ds_read_b128 v[148:151], v147
	ds_read_b128 v[152:155], v147 offset:1024
	ds_read_b128 v[156:159], v147 offset:2048
	ds_read_b128 v[164:167], v147 offset:3072
	v_add_u32_e32 v147, s56, v144
	ds_read_b128 v[168:171], v147
	ds_read_b128 v[172:175], v147 offset:1024
	ds_read_b128 v[176:179], v147 offset:2048
	ds_read_b128 v[180:183], v147 offset:3072
	s_add_u32 s50, s50, 0x40000
	s_addc_u32 s51, s51, 0
	s_mov_b32 m0, s28
	v_lshl_add_u64 v[244:245], s[50:51], 0, v[128:129]
	ds_read_b128 v[184:187], v145 offset:32768
	ds_read_b128 v[188:191], v145 offset:33792
	ds_read_b128 v[192:195], v145 offset:34816
	ds_read_b128 v[204:207], v145 offset:35840
	ds_read_b128 v[212:215], v145 offset:36864
	ds_read_b128 v[216:219], v145 offset:37888
	ds_read_b128 v[220:223], v145 offset:38912
	ds_read_b128 v[232:235], v145 offset:39936
	global_load_lds_dwordx4 v[244:245], off
	v_lshl_add_u64 v[244:245], s[50:51], 0, v[130:131]
	s_mov_b32 m0, s29
	s_nop 0
	global_load_lds_dwordx4 v[244:245], off
	s_waitcnt vmcnt(8)
	s_waitcnt lgkmcnt(0)
	s_barrier
	s_waitcnt lgkmcnt(0)
	v_mfma_f32_16x16x32_bf16 v[68:71], v[148:151], v[184:187], v[68:71]
	v_mfma_f32_16x16x32_bf16 v[64:67], v[156:159], v[184:187], v[64:67]
	v_mfma_f32_16x16x32_bf16 v[112:115], v[148:151], v[192:195], v[112:115]
	v_mfma_f32_16x16x32_bf16 v[108:111], v[156:159], v[192:195], v[108:111]
	v_mfma_f32_16x16x32_bf16 v[76:79], v[148:151], v[212:215], v[76:79]
	v_mfma_f32_16x16x32_bf16 v[72:75], v[156:159], v[212:215], v[72:75]
	v_mfma_f32_16x16x32_bf16 v[92:95], v[148:151], v[220:223], v[92:95]
	v_mfma_f32_16x16x32_bf16 v[88:91], v[156:159], v[220:223], v[88:91]
	v_mfma_f32_16x16x32_bf16 v[68:71], v[152:155], v[188:191], v[68:71]
	v_mfma_f32_16x16x32_bf16 v[64:67], v[164:167], v[188:191], v[64:67]
	v_mfma_f32_16x16x32_bf16 v[112:115], v[152:155], v[204:207], v[112:115]
	v_mfma_f32_16x16x32_bf16 v[108:111], v[164:167], v[204:207], v[108:111]
	v_mfma_f32_16x16x32_bf16 v[76:79], v[152:155], v[216:219], v[76:79]
	v_mfma_f32_16x16x32_bf16 v[72:75], v[164:167], v[216:219], v[72:75]
	v_mfma_f32_16x16x32_bf16 v[92:95], v[152:155], v[232:235], v[92:95]
	v_mfma_f32_16x16x32_bf16 v[88:91], v[164:167], v[232:235], v[88:91]
	v_mfma_f32_16x16x32_bf16 v[96:99], v[168:171], v[184:187], v[96:99]
	v_mfma_f32_16x16x32_bf16 v[100:103], v[176:179], v[184:187], v[100:103]
	v_mfma_f32_16x16x32_bf16 v[120:123], v[168:171], v[192:195], v[120:123]
	v_mfma_f32_16x16x32_bf16 v[124:127], v[176:179], v[192:195], v[124:127]
	v_mfma_f32_16x16x32_bf16 v[84:87], v[168:171], v[212:215], v[84:87]
	v_mfma_f32_16x16x32_bf16 v[80:83], v[176:179], v[212:215], v[80:83]
	v_mfma_f32_16x16x32_bf16 v[116:119], v[168:171], v[220:223], v[116:119]
	v_mfma_f32_16x16x32_bf16 v[104:107], v[176:179], v[220:223], v[104:107]
	v_mfma_f32_16x16x32_bf16 v[96:99], v[172:175], v[188:191], v[96:99]
	v_mfma_f32_16x16x32_bf16 v[100:103], v[180:183], v[188:191], v[100:103]
	v_mfma_f32_16x16x32_bf16 v[120:123], v[172:175], v[204:207], v[120:123]
	v_mfma_f32_16x16x32_bf16 v[124:127], v[180:183], v[204:207], v[124:127]
	v_mfma_f32_16x16x32_bf16 v[84:87], v[172:175], v[216:219], v[84:87]
	v_mfma_f32_16x16x32_bf16 v[80:83], v[180:183], v[216:219], v[80:83]
	v_mfma_f32_16x16x32_bf16 v[116:119], v[172:175], v[232:235], v[116:119]
	v_mfma_f32_16x16x32_bf16 v[104:107], v[180:183], v[232:235], v[104:107]
	s_barrier
	s_add_i32 s50, s55, s25
	v_lshl_add_u64 v[236:237], v[236:237], 0, s[10:11]
	s_mov_b32 m0, s50
	ds_read_b128 v[184:187], v145 offset:49152
	ds_read_b128 v[188:191], v145 offset:50176
	ds_read_b128 v[192:195], v145 offset:51200
	ds_read_b128 v[204:207], v145 offset:52224
	ds_read_b128 v[212:215], v145 offset:53248
	ds_read_b128 v[216:219], v145 offset:54272
	ds_read_b128 v[220:223], v145 offset:55296
	ds_read_b128 v[232:235], v145 offset:56320
	global_load_lds_dwordx4 v[236:237], off
	s_add_i32 m0, s50, 0x2000
	s_add_u32 s48, s48, 0x40080
	v_lshl_add_u64 v[236:237], v[238:239], 0, s[10:11]
	s_addc_u32 s49, s49, 0
	s_add_i32 s50, s56, s25
	global_load_lds_dwordx4 v[236:237], off
	v_lshl_add_u64 v[236:237], s[48:49], 0, v[196:197]
	s_mov_b32 m0, s50
	s_nop 0
	global_load_lds_dwordx4 v[236:237], off
	v_lshl_add_u64 v[236:237], s[48:49], 0, v[132:133]
	s_add_i32 m0, s50, 0x2000
	s_nop 0
	global_load_lds_dwordx4 v[236:237], off
	v_lshl_add_u64 v[236:237], v[240:241], 0, s[10:11]
	s_mov_b32 m0, s4
	s_nop 0
	global_load_lds_dwordx4 v[236:237], off
	v_lshl_add_u64 v[236:237], v[242:243], 0, s[10:11]
	s_mov_b32 m0, s31
	s_nop 0
	global_load_lds_dwordx4 v[236:237], off
	s_waitcnt vmcnt(8)
	s_waitcnt lgkmcnt(0)
	s_barrier
	s_waitcnt lgkmcnt(0)
	v_mfma_f32_16x16x32_bf16 v[60:63], v[148:151], v[184:187], v[60:63]
	v_mfma_f32_16x16x32_bf16 v[56:59], v[156:159], v[184:187], v[56:59]
	v_mfma_f32_16x16x32_bf16 v[44:47], v[148:151], v[192:195], v[44:47]
	v_mfma_f32_16x16x32_bf16 v[40:43], v[156:159], v[192:195], v[40:43]
	v_mfma_f32_16x16x32_bf16 v[28:31], v[148:151], v[212:215], v[28:31]
	v_mfma_f32_16x16x32_bf16 v[24:27], v[156:159], v[212:215], v[24:27]
	v_mfma_f32_16x16x32_bf16 v[12:15], v[148:151], v[220:223], v[12:15]
	v_mfma_f32_16x16x32_bf16 v[8:11], v[156:159], v[220:223], v[8:11]
	v_mfma_f32_16x16x32_bf16 v[60:63], v[152:155], v[188:191], v[60:63]
	v_mfma_f32_16x16x32_bf16 v[56:59], v[164:167], v[188:191], v[56:59]
	v_mfma_f32_16x16x32_bf16 v[44:47], v[152:155], v[204:207], v[44:47]
	v_mfma_f32_16x16x32_bf16 v[40:43], v[164:167], v[204:207], v[40:43]
	v_mfma_f32_16x16x32_bf16 v[28:31], v[152:155], v[216:219], v[28:31]
	v_mfma_f32_16x16x32_bf16 v[24:27], v[164:167], v[216:219], v[24:27]
	v_mfma_f32_16x16x32_bf16 v[12:15], v[152:155], v[232:235], v[12:15]
	v_mfma_f32_16x16x32_bf16 v[8:11], v[164:167], v[232:235], v[8:11]
	v_mfma_f32_16x16x32_bf16 v[52:55], v[168:171], v[184:187], v[52:55]
	v_mfma_f32_16x16x32_bf16 v[48:51], v[176:179], v[184:187], v[48:51]
	v_mfma_f32_16x16x32_bf16 v[36:39], v[168:171], v[192:195], v[36:39]
	v_mfma_f32_16x16x32_bf16 v[32:35], v[176:179], v[192:195], v[32:35]
	v_mfma_f32_16x16x32_bf16 v[20:23], v[168:171], v[212:215], v[20:23]
	v_mfma_f32_16x16x32_bf16 v[16:19], v[176:179], v[212:215], v[16:19]
	v_mfma_f32_16x16x32_bf16 v[4:7], v[168:171], v[220:223], v[4:7]
	v_mfma_f32_16x16x32_bf16 v[0:3], v[176:179], v[220:223], v[0:3]
	v_mfma_f32_16x16x32_bf16 v[52:55], v[172:175], v[188:191], v[52:55]
	v_mfma_f32_16x16x32_bf16 v[48:51], v[180:183], v[188:191], v[48:51]
	v_mfma_f32_16x16x32_bf16 v[36:39], v[172:175], v[204:207], v[36:39]
	v_mfma_f32_16x16x32_bf16 v[32:35], v[180:183], v[204:207], v[32:35]
	v_mfma_f32_16x16x32_bf16 v[20:23], v[172:175], v[216:219], v[20:23]
	v_mfma_f32_16x16x32_bf16 v[16:19], v[180:183], v[216:219], v[16:19]
	v_mfma_f32_16x16x32_bf16 v[4:7], v[172:175], v[232:235], v[4:7]
	v_mfma_f32_16x16x32_bf16 v[0:3], v[180:183], v[232:235], v[0:3]
	s_barrier
	s_add_i32 s54, s54, 2
	s_add_u32 s46, s46, 0x100
	s_addc_u32 s47, s47, 0
	s_cmp_gt_u32 s54, 13
	s_cbranch_scc0 .LBB0_701
	s_add_u32 s46, s36, 0xffffff00
	s_addc_u32 s47, s37, -1
	s_andn2_b64 vcc, exec, s[40:41]
	s_cbranch_vccnz .LBB0_704
	v_mov_b32_e32 v0, 0
	s_mov_b32 s12, s16
	s_mov_b32 s8, s18
	s_mov_b64 s[14:15], s[44:45]
	s_mov_b32 s34, s35
	v_mov_b32_e32 v1, v0
	v_mov_b32_e32 v2, v0
	v_mov_b32_e32 v3, v0
	v_mov_b32_e32 v4, v0
	v_mov_b32_e32 v5, v0
	v_mov_b32_e32 v6, v0
	v_mov_b32_e32 v7, v0
	v_mov_b32_e32 v16, v0
	v_mov_b32_e32 v17, v0
	v_mov_b32_e32 v18, v0
	v_mov_b32_e32 v19, v0
	v_mov_b32_e32 v20, v0
	v_mov_b32_e32 v21, v0
	v_mov_b32_e32 v22, v0
	v_mov_b32_e32 v23, v0
	v_mov_b32_e32 v32, v0
	v_mov_b32_e32 v33, v0
	v_mov_b32_e32 v34, v0
	v_mov_b32_e32 v35, v0
	v_mov_b32_e32 v36, v0
	v_mov_b32_e32 v37, v0
	v_mov_b32_e32 v38, v0
	v_mov_b32_e32 v39, v0
	v_mov_b32_e32 v48, v0
	v_mov_b32_e32 v49, v0
	v_mov_b32_e32 v50, v0
	v_mov_b32_e32 v51, v0
	v_mov_b32_e32 v52, v0
	v_mov_b32_e32 v53, v0
	v_mov_b32_e32 v54, v0
	v_mov_b32_e32 v55, v0
	v_mov_b32_e32 v8, v0
	v_mov_b32_e32 v9, v0
	v_mov_b32_e32 v10, v0
	v_mov_b32_e32 v11, v0
	v_mov_b32_e32 v12, v0
	v_mov_b32_e32 v13, v0
	v_mov_b32_e32 v14, v0
	v_mov_b32_e32 v15, v0
	v_mov_b32_e32 v24, v0
	v_mov_b32_e32 v25, v0
	v_mov_b32_e32 v26, v0
	v_mov_b32_e32 v27, v0
	v_mov_b32_e32 v28, v0
	v_mov_b32_e32 v29, v0
	v_mov_b32_e32 v30, v0
	v_mov_b32_e32 v31, v0
	v_mov_b32_e32 v40, v0
	v_mov_b32_e32 v41, v0
	v_mov_b32_e32 v42, v0
	v_mov_b32_e32 v43, v0
	v_mov_b32_e32 v44, v0
	v_mov_b32_e32 v45, v0
	v_mov_b32_e32 v46, v0
	v_mov_b32_e32 v47, v0
	v_mov_b32_e32 v56, v0
	v_mov_b32_e32 v57, v0
	v_mov_b32_e32 v58, v0
	v_mov_b32_e32 v59, v0
	v_mov_b32_e32 v60, v0
	v_mov_b32_e32 v61, v0
	v_mov_b32_e32 v62, v0
	v_mov_b32_e32 v63, v0
	v_mov_b32_e32 v104, v0
	v_mov_b32_e32 v105, v0
	v_mov_b32_e32 v106, v0
	v_mov_b32_e32 v107, v0
	v_mov_b32_e32 v116, v0
	v_mov_b32_e32 v117, v0
	v_mov_b32_e32 v118, v0
	v_mov_b32_e32 v119, v0
	v_mov_b32_e32 v80, v0
	v_mov_b32_e32 v81, v0
	v_mov_b32_e32 v82, v0
	v_mov_b32_e32 v83, v0
	v_mov_b32_e32 v84, v0
	v_mov_b32_e32 v85, v0
	v_mov_b32_e32 v86, v0
	v_mov_b32_e32 v87, v0
	v_mov_b32_e32 v124, v0
	v_mov_b32_e32 v125, v0
	v_mov_b32_e32 v126, v0
	v_mov_b32_e32 v127, v0
	v_mov_b32_e32 v120, v0
	v_mov_b32_e32 v121, v0
	v_mov_b32_e32 v122, v0
	v_mov_b32_e32 v123, v0
	v_mov_b32_e32 v100, v0
	v_mov_b32_e32 v101, v0
	v_mov_b32_e32 v102, v0
	v_mov_b32_e32 v103, v0
	v_mov_b32_e32 v96, v0
	v_mov_b32_e32 v97, v0
	v_mov_b32_e32 v98, v0
	v_mov_b32_e32 v99, v0
	v_mov_b32_e32 v88, v0
	v_mov_b32_e32 v89, v0
	v_mov_b32_e32 v90, v0
	v_mov_b32_e32 v91, v0
	v_mov_b32_e32 v92, v0
	v_mov_b32_e32 v93, v0
	v_mov_b32_e32 v94, v0
	v_mov_b32_e32 v95, v0
	v_mov_b32_e32 v72, v0
	v_mov_b32_e32 v73, v0
	v_mov_b32_e32 v74, v0
	v_mov_b32_e32 v75, v0
	v_mov_b32_e32 v76, v0
	v_mov_b32_e32 v77, v0
	v_mov_b32_e32 v78, v0
	v_mov_b32_e32 v79, v0
	v_mov_b32_e32 v108, v0
	v_mov_b32_e32 v109, v0
	v_mov_b32_e32 v110, v0
	v_mov_b32_e32 v111, v0
	v_mov_b32_e32 v112, v0
	v_mov_b32_e32 v113, v0
	v_mov_b32_e32 v114, v0
	v_mov_b32_e32 v115, v0
	v_mov_b32_e32 v64, v0
	v_mov_b32_e32 v65, v0
	v_mov_b32_e32 v66, v0
	v_mov_b32_e32 v67, v0
	v_mov_b32_e32 v68, v0
	v_mov_b32_e32 v69, v0
	v_mov_b32_e32 v70, v0
	v_mov_b32_e32 v71, v0
	s_movk_i32 s52, 0x1fff
	s_mov_b32 s53, 0x7ffff
	s_andn2_b64 vcc, exec, s[38:39]
	s_cbranch_vccnz .LBB0_705
	s_branch .LBB0_706

.LBB0_799:
	s_add_u32 s48, s46, 0xfffc0080
	s_addc_u32 s49, s47, -1
	s_add_i32 s52, 0, 0x10000
	s_cmp_eq_u32 s45, 12
	s_cselect_b32 s51, s19, s49
	s_cselect_b32 s50, s34, s48
	s_cselect_b32 s49, s17, s37
	s_cselect_b32 s48, s35, s36
	s_add_i32 s54, 0, 0x14000
	v_add_u32_e32 v154, s52, v139
	v_add_u32_e32 v158, s54, v139
	ds_read_b128 v[142:145], v154
	ds_read_b128 v[146:149], v154 offset:1024
	ds_read_b128 v[150:153], v154 offset:2048
	ds_read_b128 v[154:157], v154 offset:3072
	ds_read_b128 v[164:167], v158
	ds_read_b128 v[168:171], v158 offset:1024
	ds_read_b128 v[172:175], v158 offset:2048
	ds_read_b128 v[176:179], v158 offset:3072
	v_lshl_add_u64 v[158:159], s[46:47], 0, v[134:135]
	s_add_i32 m0, s24, 0xc000
	ds_read_b128 v[180:183], v141
	ds_read_b128 v[184:187], v141 offset:1024
	ds_read_b128 v[188:191], v141 offset:2048
	ds_read_b128 v[192:195], v141 offset:3072
	ds_read_b128 v[204:207], v141 offset:4096
	ds_read_b128 v[212:215], v141 offset:5120
	ds_read_b128 v[216:219], v141 offset:6144
	ds_read_b128 v[220:223], v141 offset:7168
	global_load_lds_dwordx4 v[158:159], off
	v_lshl_add_u64 v[158:159], s[46:47], 0, v[136:137]
	s_add_i32 m0, s24, 0xe000
	s_nop 0
	global_load_lds_dwordx4 v[158:159], off
	s_waitcnt vmcnt(8)
	s_waitcnt lgkmcnt(0)
	s_barrier
	s_waitcnt lgkmcnt(0)
	v_mfma_f32_16x16x32_bf16 v[124:127], v[142:145], v[180:183], v[124:127]
	v_mfma_f32_16x16x32_bf16 v[116:119], v[150:153], v[180:183], v[116:119]
	v_mfma_f32_16x16x32_bf16 v[108:111], v[142:145], v[188:191], v[108:111]
	v_mfma_f32_16x16x32_bf16 v[100:103], v[150:153], v[188:191], v[100:103]
	v_mfma_f32_16x16x32_bf16 v[92:95], v[142:145], v[204:207], v[92:95]
	v_mfma_f32_16x16x32_bf16 v[84:87], v[150:153], v[204:207], v[84:87]
	v_mfma_f32_16x16x32_bf16 v[76:79], v[142:145], v[216:219], v[76:79]
	v_mfma_f32_16x16x32_bf16 v[68:71], v[150:153], v[216:219], v[68:71]
	v_mfma_f32_16x16x32_bf16 v[124:127], v[146:149], v[184:187], v[124:127]
	v_mfma_f32_16x16x32_bf16 v[116:119], v[154:157], v[184:187], v[116:119]
	v_mfma_f32_16x16x32_bf16 v[108:111], v[146:149], v[192:195], v[108:111]
	v_mfma_f32_16x16x32_bf16 v[100:103], v[154:157], v[192:195], v[100:103]
	v_mfma_f32_16x16x32_bf16 v[92:95], v[146:149], v[212:215], v[92:95]
	v_mfma_f32_16x16x32_bf16 v[84:87], v[154:157], v[212:215], v[84:87]
	v_mfma_f32_16x16x32_bf16 v[76:79], v[146:149], v[220:223], v[76:79]
	v_mfma_f32_16x16x32_bf16 v[68:71], v[154:157], v[220:223], v[68:71]
	v_mfma_f32_16x16x32_bf16 v[120:123], v[164:167], v[180:183], v[120:123]
	v_mfma_f32_16x16x32_bf16 v[112:115], v[172:175], v[180:183], v[112:115]
	v_mfma_f32_16x16x32_bf16 v[104:107], v[164:167], v[188:191], v[104:107]
	v_mfma_f32_16x16x32_bf16 v[96:99], v[172:175], v[188:191], v[96:99]
	v_mfma_f32_16x16x32_bf16 v[88:91], v[164:167], v[204:207], v[88:91]
	v_mfma_f32_16x16x32_bf16 v[80:83], v[172:175], v[204:207], v[80:83]
	v_mfma_f32_16x16x32_bf16 v[72:75], v[164:167], v[216:219], v[72:75]
	v_mfma_f32_16x16x32_bf16 v[64:67], v[172:175], v[216:219], v[64:67]
	v_mfma_f32_16x16x32_bf16 v[120:123], v[168:171], v[184:187], v[120:123]
	v_mfma_f32_16x16x32_bf16 v[112:115], v[176:179], v[184:187], v[112:115]
	v_mfma_f32_16x16x32_bf16 v[104:107], v[168:171], v[192:195], v[104:107]
	v_mfma_f32_16x16x32_bf16 v[96:99], v[176:179], v[192:195], v[96:99]
	v_mfma_f32_16x16x32_bf16 v[88:91], v[168:171], v[212:215], v[88:91]
	v_mfma_f32_16x16x32_bf16 v[80:83], v[176:179], v[212:215], v[80:83]
	v_mfma_f32_16x16x32_bf16 v[72:75], v[168:171], v[220:223], v[72:75]
	v_mfma_f32_16x16x32_bf16 v[64:67], v[176:179], v[220:223], v[64:67]
	s_barrier
	s_add_i32 s52, s52, s22
	v_lshl_add_u64 v[158:159], s[48:49], 0, v[196:197]
	s_mov_b32 m0, s52
	ds_read_b128 v[180:183], v141 offset:16384
	ds_read_b128 v[184:187], v141 offset:17408
	ds_read_b128 v[188:191], v141 offset:18432
	ds_read_b128 v[192:195], v141 offset:19456
	ds_read_b128 v[204:207], v141 offset:20480
	ds_read_b128 v[212:215], v141 offset:21504
	ds_read_b128 v[216:219], v141 offset:22528
	ds_read_b128 v[220:223], v141 offset:23552
	global_load_lds_dwordx4 v[158:159], off
	s_add_i32 m0, s52, 0x2000
	s_add_u32 s52, s48, 0x40000
	v_lshl_add_u64 v[232:233], s[48:49], 0, v[128:129]
	s_addc_u32 s53, s49, 0
	s_add_i32 s54, s54, s22
	global_load_lds_dwordx4 v[232:233], off
	v_lshl_add_u64 v[234:235], s[52:53], 0, v[196:197]
	s_mov_b32 m0, s54
	v_lshl_add_u64 v[236:237], s[50:51], 0, v[130:131]
	global_load_lds_dwordx4 v[234:235], off
	v_lshl_add_u64 v[234:235], s[52:53], 0, v[128:129]
	s_add_i32 m0, s54, 0x2000
	s_nop 0
	global_load_lds_dwordx4 v[234:235], off
	v_lshl_add_u64 v[234:235], s[50:51], 0, v[132:133]
	s_mov_b32 m0, s24
	s_nop 0
	global_load_lds_dwordx4 v[234:235], off
	s_mov_b32 m0, s25
	s_nop 0
	global_load_lds_dwordx4 v[236:237], off
	s_waitcnt vmcnt(8)
	s_waitcnt lgkmcnt(0)
	s_barrier
	s_waitcnt lgkmcnt(0)
	v_mfma_f32_16x16x32_bf16 v[60:63], v[142:145], v[180:183], v[60:63]
	v_mfma_f32_16x16x32_bf16 v[52:55], v[150:153], v[180:183], v[52:55]
	v_mfma_f32_16x16x32_bf16 v[44:47], v[142:145], v[188:191], v[44:47]
	v_mfma_f32_16x16x32_bf16 v[36:39], v[150:153], v[188:191], v[36:39]
	v_mfma_f32_16x16x32_bf16 v[28:31], v[142:145], v[204:207], v[28:31]
	v_mfma_f32_16x16x32_bf16 v[20:23], v[150:153], v[204:207], v[20:23]
	v_mfma_f32_16x16x32_bf16 v[12:15], v[142:145], v[216:219], v[12:15]
	v_mfma_f32_16x16x32_bf16 v[4:7], v[150:153], v[216:219], v[4:7]
	v_mfma_f32_16x16x32_bf16 v[60:63], v[146:149], v[184:187], v[60:63]
	v_mfma_f32_16x16x32_bf16 v[52:55], v[154:157], v[184:187], v[52:55]
	v_mfma_f32_16x16x32_bf16 v[44:47], v[146:149], v[192:195], v[44:47]
	v_mfma_f32_16x16x32_bf16 v[36:39], v[154:157], v[192:195], v[36:39]
	v_mfma_f32_16x16x32_bf16 v[28:31], v[146:149], v[212:215], v[28:31]
	v_mfma_f32_16x16x32_bf16 v[20:23], v[154:157], v[212:215], v[20:23]
	v_mfma_f32_16x16x32_bf16 v[12:15], v[146:149], v[220:223], v[12:15]
	v_mfma_f32_16x16x32_bf16 v[4:7], v[154:157], v[220:223], v[4:7]
	v_mfma_f32_16x16x32_bf16 v[56:59], v[164:167], v[180:183], v[56:59]
	v_mfma_f32_16x16x32_bf16 v[48:51], v[172:175], v[180:183], v[48:51]
	v_mfma_f32_16x16x32_bf16 v[40:43], v[164:167], v[188:191], v[40:43]
	v_mfma_f32_16x16x32_bf16 v[32:35], v[172:175], v[188:191], v[32:35]
	v_mfma_f32_16x16x32_bf16 v[24:27], v[164:167], v[204:207], v[24:27]
	v_mfma_f32_16x16x32_bf16 v[16:19], v[172:175], v[204:207], v[16:19]
	v_mfma_f32_16x16x32_bf16 v[8:11], v[164:167], v[216:219], v[8:11]
	v_mfma_f32_16x16x32_bf16 v[0:3], v[172:175], v[216:219], v[0:3]
	v_mfma_f32_16x16x32_bf16 v[56:59], v[168:171], v[184:187], v[56:59]
	v_mfma_f32_16x16x32_bf16 v[48:51], v[176:179], v[184:187], v[48:51]
	v_mfma_f32_16x16x32_bf16 v[40:43], v[168:171], v[192:195], v[40:43]
	v_mfma_f32_16x16x32_bf16 v[32:35], v[176:179], v[192:195], v[32:35]
	v_mfma_f32_16x16x32_bf16 v[24:27], v[168:171], v[212:215], v[24:27]
	v_mfma_f32_16x16x32_bf16 v[16:19], v[176:179], v[212:215], v[16:19]
	v_mfma_f32_16x16x32_bf16 v[8:11], v[168:171], v[220:223], v[8:11]
	v_mfma_f32_16x16x32_bf16 v[0:3], v[176:179], v[220:223], v[0:3]
	s_barrier
	s_add_i32 s52, 0, 0x18000
	s_add_i32 s53, 0, 0x1c000
	v_add_u32_e32 v154, s52, v139
	v_add_u32_e32 v176, s53, v139
	ds_read_b128 v[142:145], v154
	ds_read_b128 v[146:149], v154 offset:1024
	ds_read_b128 v[150:153], v154 offset:2048
	ds_read_b128 v[154:157], v154 offset:3072
	ds_read_b128 v[164:167], v176
	ds_read_b128 v[168:171], v176 offset:1024
	ds_read_b128 v[172:175], v176 offset:2048
	ds_read_b128 v[176:179], v176 offset:3072
	s_add_u32 s50, s50, 0x40000
	s_addc_u32 s51, s51, 0
	s_mov_b32 m0, s26
	v_lshl_add_u64 v[238:239], s[50:51], 0, v[132:133]
	ds_read_b128 v[180:183], v141 offset:32768
	ds_read_b128 v[184:187], v141 offset:33792
	ds_read_b128 v[188:191], v141 offset:34816
	ds_read_b128 v[192:195], v141 offset:35840
	ds_read_b128 v[204:207], v141 offset:36864
	ds_read_b128 v[212:215], v141 offset:37888
	ds_read_b128 v[216:219], v141 offset:38912
	ds_read_b128 v[220:223], v141 offset:39936
	global_load_lds_dwordx4 v[238:239], off
	v_lshl_add_u64 v[238:239], s[50:51], 0, v[130:131]
	s_mov_b32 m0, s27
	s_nop 0
	global_load_lds_dwordx4 v[238:239], off
	s_waitcnt vmcnt(8)
	s_waitcnt lgkmcnt(0)
	s_barrier
	s_waitcnt lgkmcnt(0)
	v_mfma_f32_16x16x32_bf16 v[124:127], v[142:145], v[180:183], v[124:127]
	v_mfma_f32_16x16x32_bf16 v[116:119], v[150:153], v[180:183], v[116:119]
	v_mfma_f32_16x16x32_bf16 v[108:111], v[142:145], v[188:191], v[108:111]
	v_mfma_f32_16x16x32_bf16 v[100:103], v[150:153], v[188:191], v[100:103]
	v_mfma_f32_16x16x32_bf16 v[92:95], v[142:145], v[204:207], v[92:95]
	v_mfma_f32_16x16x32_bf16 v[84:87], v[150:153], v[204:207], v[84:87]
	v_mfma_f32_16x16x32_bf16 v[76:79], v[142:145], v[216:219], v[76:79]
	v_mfma_f32_16x16x32_bf16 v[68:71], v[150:153], v[216:219], v[68:71]
	v_mfma_f32_16x16x32_bf16 v[124:127], v[146:149], v[184:187], v[124:127]
	v_mfma_f32_16x16x32_bf16 v[116:119], v[154:157], v[184:187], v[116:119]
	v_mfma_f32_16x16x32_bf16 v[108:111], v[146:149], v[192:195], v[108:111]
	v_mfma_f32_16x16x32_bf16 v[100:103], v[154:157], v[192:195], v[100:103]
	v_mfma_f32_16x16x32_bf16 v[92:95], v[146:149], v[212:215], v[92:95]
	v_mfma_f32_16x16x32_bf16 v[84:87], v[154:157], v[212:215], v[84:87]
	v_mfma_f32_16x16x32_bf16 v[76:79], v[146:149], v[220:223], v[76:79]
	v_mfma_f32_16x16x32_bf16 v[68:71], v[154:157], v[220:223], v[68:71]
	v_mfma_f32_16x16x32_bf16 v[120:123], v[164:167], v[180:183], v[120:123]
	v_mfma_f32_16x16x32_bf16 v[112:115], v[172:175], v[180:183], v[112:115]
	v_mfma_f32_16x16x32_bf16 v[104:107], v[164:167], v[188:191], v[104:107]
	v_mfma_f32_16x16x32_bf16 v[96:99], v[172:175], v[188:191], v[96:99]
	v_mfma_f32_16x16x32_bf16 v[88:91], v[164:167], v[204:207], v[88:91]
	v_mfma_f32_16x16x32_bf16 v[80:83], v[172:175], v[204:207], v[80:83]
	v_mfma_f32_16x16x32_bf16 v[72:75], v[164:167], v[216:219], v[72:75]
	v_mfma_f32_16x16x32_bf16 v[64:67], v[172:175], v[216:219], v[64:67]
	v_mfma_f32_16x16x32_bf16 v[120:123], v[168:171], v[184:187], v[120:123]
	v_mfma_f32_16x16x32_bf16 v[112:115], v[176:179], v[184:187], v[112:115]
	v_mfma_f32_16x16x32_bf16 v[104:107], v[168:171], v[192:195], v[104:107]
	v_mfma_f32_16x16x32_bf16 v[96:99], v[176:179], v[192:195], v[96:99]
	v_mfma_f32_16x16x32_bf16 v[88:91], v[168:171], v[212:215], v[88:91]
	v_mfma_f32_16x16x32_bf16 v[80:83], v[176:179], v[212:215], v[80:83]
	v_mfma_f32_16x16x32_bf16 v[72:75], v[168:171], v[220:223], v[72:75]
	v_mfma_f32_16x16x32_bf16 v[64:67], v[176:179], v[220:223], v[64:67]
	s_barrier
	s_add_i32 s50, s52, s22
	v_lshl_add_u64 v[158:159], v[158:159], 0, s[10:11]
	s_mov_b32 m0, s50
	ds_read_b128 v[180:183], v141 offset:49152
	ds_read_b128 v[184:187], v141 offset:50176
	ds_read_b128 v[188:191], v141 offset:51200
	ds_read_b128 v[192:195], v141 offset:52224
	ds_read_b128 v[204:207], v141 offset:53248
	ds_read_b128 v[212:215], v141 offset:54272
	ds_read_b128 v[216:219], v141 offset:55296
	ds_read_b128 v[220:223], v141 offset:56320
	global_load_lds_dwordx4 v[158:159], off
	s_add_i32 m0, s50, 0x2000
	s_add_u32 s48, s48, 0x40080
	v_lshl_add_u64 v[158:159], v[232:233], 0, s[10:11]
	s_addc_u32 s49, s49, 0
	s_add_i32 s50, s53, s22
	global_load_lds_dwordx4 v[158:159], off
	v_lshl_add_u64 v[158:159], s[48:49], 0, v[196:197]
	s_mov_b32 m0, s50
	s_nop 0
	global_load_lds_dwordx4 v[158:159], off
	v_lshl_add_u64 v[158:159], s[48:49], 0, v[128:129]
	s_add_i32 m0, s50, 0x2000
	s_nop 0
	global_load_lds_dwordx4 v[158:159], off
	v_lshl_add_u64 v[158:159], v[234:235], 0, s[10:11]
	s_mov_b32 m0, s4
	s_nop 0
	global_load_lds_dwordx4 v[158:159], off
	v_lshl_add_u64 v[158:159], v[236:237], 0, s[10:11]
	s_mov_b32 m0, s28
	s_nop 0
	global_load_lds_dwordx4 v[158:159], off
	s_waitcnt vmcnt(8)
	s_waitcnt lgkmcnt(0)
	s_barrier
	s_waitcnt lgkmcnt(0)
	v_mfma_f32_16x16x32_bf16 v[60:63], v[142:145], v[180:183], v[60:63]
	v_mfma_f32_16x16x32_bf16 v[52:55], v[150:153], v[180:183], v[52:55]
	v_mfma_f32_16x16x32_bf16 v[44:47], v[142:145], v[188:191], v[44:47]
	v_mfma_f32_16x16x32_bf16 v[36:39], v[150:153], v[188:191], v[36:39]
	v_mfma_f32_16x16x32_bf16 v[28:31], v[142:145], v[204:207], v[28:31]
	v_mfma_f32_16x16x32_bf16 v[20:23], v[150:153], v[204:207], v[20:23]
	v_mfma_f32_16x16x32_bf16 v[12:15], v[142:145], v[216:219], v[12:15]
	v_mfma_f32_16x16x32_bf16 v[4:7], v[150:153], v[216:219], v[4:7]
	v_mfma_f32_16x16x32_bf16 v[60:63], v[146:149], v[184:187], v[60:63]
	v_mfma_f32_16x16x32_bf16 v[52:55], v[154:157], v[184:187], v[52:55]
	v_mfma_f32_16x16x32_bf16 v[44:47], v[146:149], v[192:195], v[44:47]
	v_mfma_f32_16x16x32_bf16 v[36:39], v[154:157], v[192:195], v[36:39]
	v_mfma_f32_16x16x32_bf16 v[28:31], v[146:149], v[212:215], v[28:31]
	v_mfma_f32_16x16x32_bf16 v[20:23], v[154:157], v[212:215], v[20:23]
	v_mfma_f32_16x16x32_bf16 v[12:15], v[146:149], v[220:223], v[12:15]
	v_mfma_f32_16x16x32_bf16 v[4:7], v[154:157], v[220:223], v[4:7]
	v_mfma_f32_16x16x32_bf16 v[56:59], v[164:167], v[180:183], v[56:59]
	v_mfma_f32_16x16x32_bf16 v[48:51], v[172:175], v[180:183], v[48:51]
	v_mfma_f32_16x16x32_bf16 v[40:43], v[164:167], v[188:191], v[40:43]
	v_mfma_f32_16x16x32_bf16 v[32:35], v[172:175], v[188:191], v[32:35]
	v_mfma_f32_16x16x32_bf16 v[24:27], v[164:167], v[204:207], v[24:27]
	v_mfma_f32_16x16x32_bf16 v[16:19], v[172:175], v[204:207], v[16:19]
	v_mfma_f32_16x16x32_bf16 v[8:11], v[164:167], v[216:219], v[8:11]
	v_mfma_f32_16x16x32_bf16 v[0:3], v[172:175], v[216:219], v[0:3]
	v_mfma_f32_16x16x32_bf16 v[56:59], v[168:171], v[184:187], v[56:59]
	v_mfma_f32_16x16x32_bf16 v[48:51], v[176:179], v[184:187], v[48:51]
	v_mfma_f32_16x16x32_bf16 v[40:43], v[168:171], v[192:195], v[40:43]
	v_mfma_f32_16x16x32_bf16 v[32:35], v[176:179], v[192:195], v[32:35]
	v_mfma_f32_16x16x32_bf16 v[24:27], v[168:171], v[212:215], v[24:27]
	v_mfma_f32_16x16x32_bf16 v[16:19], v[176:179], v[212:215], v[16:19]
	v_mfma_f32_16x16x32_bf16 v[8:11], v[168:171], v[220:223], v[8:11]
	v_mfma_f32_16x16x32_bf16 v[0:3], v[176:179], v[220:223], v[0:3]
	s_barrier
	s_add_i32 s45, s45, 2
	s_add_u32 s46, s46, 0x100
	s_addc_u32 s47, s47, 0
	s_add_u32 s36, s36, 0x100
	s_addc_u32 s37, s37, 0
	s_cmp_gt_u32 s45, 13
	s_cbranch_scc0 .LBB0_799
	s_and_b64 vcc, exec, s[14:15]
	s_cbranch_vccz .LBB0_802
	s_barrier

.LBB0_823:
	s_add_u32 s41, s46, s36
	s_addc_u32 s58, s47, 0
	s_add_u32 s37, s41, 0x100
	s_addc_u32 s54, s58, 0
	s_and_b64 s[52:53], s[50:51], exec
	s_cselect_b32 s55, s17, s54
	s_cselect_b32 s54, s34, s37
	s_add_u32 s36, s44, s36
	s_addc_u32 s37, s45, 0
	s_add_u32 s52, s36, 0x100
	s_addc_u32 s53, s37, 0
	s_add_i32 s67, 0, 0x10000
	s_and_b64 s[36:37], s[50:51], exec
	s_cselect_b32 s57, s15, s53
	s_cselect_b32 s56, s35, s52
	s_add_i32 s51, 0, 0x14000
	s_add_u32 s60, s41, 0x10080
	s_addc_u32 s61, s58, 0
	s_add_i32 s66, s67, s21
	s_add_i32 m0, s24, 0xc000
	s_add_i32 s69, s24, 0xe000
	s_add_i32 s63, s66, 0x2000
	v_add_u32_e32 v134, s67, v137
	s_add_u32 s58, s56, 0x10000
	ds_read_b128 v[140:143], v134
	ds_read_b128 v[144:147], v134 offset:1024
	ds_read_b128 v[148:151], v134 offset:2048
	ds_read_b128 v[152:155], v134 offset:3072
	v_add_u32_e32 v134, s51, v137
	s_addc_u32 s59, s57, 0
	s_add_i32 s65, s51, s21
	ds_read_b128 v[156:159], v134
	ds_read_b128 v[164:167], v134 offset:1024
	ds_read_b128 v[168:171], v134 offset:2048
	ds_read_b128 v[172:175], v134 offset:3072
	s_add_i32 s64, s65, 0x2000
	s_add_i32 s62, 0, 0x18000
	s_add_i32 s41, 0, 0x1c000
	s_add_u32 s52, s54, 0x10000
	s_addc_u32 s53, s55, 0
	s_add_i32 s37, s62, s21
	s_add_i32 s36, s37, 0x2000
	s_add_u32 s50, s56, 0x10080
	s_addc_u32 s51, s57, 0
	s_add_i32 s68, s41, s21
	s_add_i32 s67, s68, 0x2000
	v_lshl_add_u64 v[134:135], s[60:61], 0, v[128:129]
	ds_read_b128 v[176:179], v139
	ds_read_b128 v[180:183], v139 offset:1024
	ds_read_b128 v[184:187], v139 offset:2048
	ds_read_b128 v[188:191], v139 offset:3072
	ds_read_b128 v[192:195], v139 offset:4096
	ds_read_b128 v[204:207], v139 offset:5120
	ds_read_b128 v[212:215], v139 offset:6144
	ds_read_b128 v[216:219], v139 offset:7168
	global_load_lds_dwordx4 v[134:135], off
	v_lshl_add_u64 v[134:135], s[60:61], 0, v[130:131]
	s_mov_b32 m0, s69
	s_nop 0
	global_load_lds_dwordx4 v[134:135], off
	s_waitcnt vmcnt(8)
	s_waitcnt lgkmcnt(0)
	s_barrier
	s_waitcnt lgkmcnt(0)
	v_mfma_f32_16x16x32_bf16 v[124:127], v[140:143], v[176:179], v[124:127]
	v_mfma_f32_16x16x32_bf16 v[120:123], v[148:151], v[176:179], v[120:123]
	v_mfma_f32_16x16x32_bf16 v[116:119], v[140:143], v[184:187], v[116:119]
	v_mfma_f32_16x16x32_bf16 v[108:111], v[148:151], v[184:187], v[108:111]
	v_mfma_f32_16x16x32_bf16 v[100:103], v[140:143], v[192:195], v[100:103]
	v_mfma_f32_16x16x32_bf16 v[92:95], v[148:151], v[192:195], v[92:95]
	v_mfma_f32_16x16x32_bf16 v[84:87], v[140:143], v[212:215], v[84:87]
	v_mfma_f32_16x16x32_bf16 v[76:79], v[148:151], v[212:215], v[76:79]
	v_mfma_f32_16x16x32_bf16 v[124:127], v[144:147], v[180:183], v[124:127]
	v_mfma_f32_16x16x32_bf16 v[120:123], v[152:155], v[180:183], v[120:123]
	v_mfma_f32_16x16x32_bf16 v[116:119], v[144:147], v[188:191], v[116:119]
	v_mfma_f32_16x16x32_bf16 v[108:111], v[152:155], v[188:191], v[108:111]
	v_mfma_f32_16x16x32_bf16 v[100:103], v[144:147], v[204:207], v[100:103]
	v_mfma_f32_16x16x32_bf16 v[92:95], v[152:155], v[204:207], v[92:95]
	v_mfma_f32_16x16x32_bf16 v[84:87], v[144:147], v[216:219], v[84:87]
	v_mfma_f32_16x16x32_bf16 v[76:79], v[152:155], v[216:219], v[76:79]
	v_mfma_f32_16x16x32_bf16 v[112:115], v[156:159], v[176:179], v[112:115]
	v_mfma_f32_16x16x32_bf16 v[104:107], v[168:171], v[176:179], v[104:107]
	v_mfma_f32_16x16x32_bf16 v[96:99], v[156:159], v[184:187], v[96:99]
	v_mfma_f32_16x16x32_bf16 v[88:91], v[168:171], v[184:187], v[88:91]
	v_mfma_f32_16x16x32_bf16 v[80:83], v[156:159], v[192:195], v[80:83]
	v_mfma_f32_16x16x32_bf16 v[72:75], v[168:171], v[192:195], v[72:75]
	v_mfma_f32_16x16x32_bf16 v[68:71], v[156:159], v[212:215], v[68:71]
	v_mfma_f32_16x16x32_bf16 v[64:67], v[168:171], v[212:215], v[64:67]
	v_mfma_f32_16x16x32_bf16 v[112:115], v[164:167], v[180:183], v[112:115]
	v_mfma_f32_16x16x32_bf16 v[104:107], v[172:175], v[180:183], v[104:107]
	v_mfma_f32_16x16x32_bf16 v[96:99], v[164:167], v[188:191], v[96:99]
	v_mfma_f32_16x16x32_bf16 v[88:91], v[172:175], v[188:191], v[88:91]
	v_mfma_f32_16x16x32_bf16 v[80:83], v[164:167], v[204:207], v[80:83]
	v_mfma_f32_16x16x32_bf16 v[72:75], v[172:175], v[204:207], v[72:75]
	v_mfma_f32_16x16x32_bf16 v[68:71], v[164:167], v[216:219], v[68:71]
	v_mfma_f32_16x16x32_bf16 v[64:67], v[172:175], v[216:219], v[64:67]
	s_barrier
	s_mov_b32 m0, s66
	v_lshl_add_u64 v[134:135], s[56:57], 0, v[196:197]
	ds_read_b128 v[176:179], v139 offset:16384
	ds_read_b128 v[180:183], v139 offset:17408
	ds_read_b128 v[184:187], v139 offset:18432
	ds_read_b128 v[188:191], v139 offset:19456
	ds_read_b128 v[192:195], v139 offset:20480
	ds_read_b128 v[204:207], v139 offset:21504
	ds_read_b128 v[212:215], v139 offset:22528
	ds_read_b128 v[216:219], v139 offset:23552
	global_load_lds_dwordx4 v[134:135], off
	v_lshl_add_u64 v[220:221], s[56:57], 0, v[132:133]
	s_mov_b32 m0, s63
	v_lshl_add_u64 v[222:223], s[58:59], 0, v[196:197]
	global_load_lds_dwordx4 v[220:221], off
	s_mov_b32 m0, s65
	v_lshl_add_u64 v[232:233], s[54:55], 0, v[130:131]
	global_load_lds_dwordx4 v[222:223], off
	v_lshl_add_u64 v[222:223], s[58:59], 0, v[132:133]
	s_mov_b32 m0, s64
	s_nop 0
	global_load_lds_dwordx4 v[222:223], off
	v_lshl_add_u64 v[222:223], s[54:55], 0, v[128:129]
	s_mov_b32 m0, s24
	s_nop 0
	global_load_lds_dwordx4 v[222:223], off
	s_mov_b32 m0, s25
	s_nop 0
	global_load_lds_dwordx4 v[232:233], off
	s_waitcnt vmcnt(8)
	s_waitcnt lgkmcnt(0)
	s_barrier
	s_waitcnt lgkmcnt(0)
	v_mfma_f32_16x16x32_bf16 v[60:63], v[140:143], v[176:179], v[60:63]
	v_mfma_f32_16x16x32_bf16 v[56:59], v[148:151], v[176:179], v[56:59]
	v_mfma_f32_16x16x32_bf16 v[52:55], v[140:143], v[184:187], v[52:55]
	v_mfma_f32_16x16x32_bf16 v[44:47], v[148:151], v[184:187], v[44:47]
	v_mfma_f32_16x16x32_bf16 v[36:39], v[140:143], v[192:195], v[36:39]
	v_mfma_f32_16x16x32_bf16 v[28:31], v[148:151], v[192:195], v[28:31]
	v_mfma_f32_16x16x32_bf16 v[20:23], v[140:143], v[212:215], v[20:23]
	v_mfma_f32_16x16x32_bf16 v[12:15], v[148:151], v[212:215], v[12:15]
	v_mfma_f32_16x16x32_bf16 v[60:63], v[144:147], v[180:183], v[60:63]
	v_mfma_f32_16x16x32_bf16 v[56:59], v[152:155], v[180:183], v[56:59]
	v_mfma_f32_16x16x32_bf16 v[52:55], v[144:147], v[188:191], v[52:55]
	v_mfma_f32_16x16x32_bf16 v[44:47], v[152:155], v[188:191], v[44:47]
	v_mfma_f32_16x16x32_bf16 v[36:39], v[144:147], v[204:207], v[36:39]
	v_mfma_f32_16x16x32_bf16 v[28:31], v[152:155], v[204:207], v[28:31]
	v_mfma_f32_16x16x32_bf16 v[20:23], v[144:147], v[216:219], v[20:23]
	v_mfma_f32_16x16x32_bf16 v[12:15], v[152:155], v[216:219], v[12:15]
	v_mfma_f32_16x16x32_bf16 v[48:51], v[156:159], v[176:179], v[48:51]
	v_mfma_f32_16x16x32_bf16 v[40:43], v[168:171], v[176:179], v[40:43]
	v_mfma_f32_16x16x32_bf16 v[32:35], v[156:159], v[184:187], v[32:35]
	v_mfma_f32_16x16x32_bf16 v[24:27], v[168:171], v[184:187], v[24:27]
	v_mfma_f32_16x16x32_bf16 v[16:19], v[156:159], v[192:195], v[16:19]
	v_mfma_f32_16x16x32_bf16 v[8:11], v[168:171], v[192:195], v[8:11]
	v_mfma_f32_16x16x32_bf16 v[4:7], v[156:159], v[212:215], v[4:7]
	v_mfma_f32_16x16x32_bf16 v[0:3], v[168:171], v[212:215], v[0:3]
	v_mfma_f32_16x16x32_bf16 v[48:51], v[164:167], v[180:183], v[48:51]
	v_mfma_f32_16x16x32_bf16 v[40:43], v[172:175], v[180:183], v[40:43]
	v_mfma_f32_16x16x32_bf16 v[32:35], v[164:167], v[188:191], v[32:35]
	v_mfma_f32_16x16x32_bf16 v[24:27], v[172:175], v[188:191], v[24:27]
	v_mfma_f32_16x16x32_bf16 v[16:19], v[164:167], v[204:207], v[16:19]
	v_mfma_f32_16x16x32_bf16 v[8:11], v[172:175], v[204:207], v[8:11]
	v_mfma_f32_16x16x32_bf16 v[4:7], v[164:167], v[216:219], v[4:7]
	v_mfma_f32_16x16x32_bf16 v[0:3], v[172:175], v[216:219], v[0:3]
	s_barrier
	v_add_u32_e32 v152, s62, v137
	v_add_u32_e32 v172, s41, v137
	ds_read_b128 v[140:143], v152
	ds_read_b128 v[144:147], v152 offset:1024
	ds_read_b128 v[148:151], v152 offset:2048
	ds_read_b128 v[152:155], v152 offset:3072
	ds_read_b128 v[156:159], v172
	ds_read_b128 v[164:167], v172 offset:1024
	ds_read_b128 v[168:171], v172 offset:2048
	ds_read_b128 v[172:175], v172 offset:3072
	s_mov_b32 m0, s26
	v_lshl_add_u64 v[234:235], s[52:53], 0, v[128:129]
	ds_read_b128 v[176:179], v139 offset:32768
	ds_read_b128 v[180:183], v139 offset:33792
	ds_read_b128 v[184:187], v139 offset:34816
	ds_read_b128 v[188:191], v139 offset:35840
	ds_read_b128 v[192:195], v139 offset:36864
	ds_read_b128 v[204:207], v139 offset:37888
	ds_read_b128 v[212:215], v139 offset:38912
	ds_read_b128 v[216:219], v139 offset:39936
	global_load_lds_dwordx4 v[234:235], off
	v_lshl_add_u64 v[234:235], s[52:53], 0, v[130:131]
	s_mov_b32 m0, s27
	s_nop 0
	global_load_lds_dwordx4 v[234:235], off
	s_waitcnt vmcnt(8)
	s_waitcnt lgkmcnt(0)
	s_barrier
	s_waitcnt lgkmcnt(0)
	v_mfma_f32_16x16x32_bf16 v[124:127], v[140:143], v[176:179], v[124:127]
	v_mfma_f32_16x16x32_bf16 v[120:123], v[148:151], v[176:179], v[120:123]
	v_mfma_f32_16x16x32_bf16 v[116:119], v[140:143], v[184:187], v[116:119]
	v_mfma_f32_16x16x32_bf16 v[108:111], v[148:151], v[184:187], v[108:111]
	v_mfma_f32_16x16x32_bf16 v[100:103], v[140:143], v[192:195], v[100:103]
	v_mfma_f32_16x16x32_bf16 v[92:95], v[148:151], v[192:195], v[92:95]
	v_mfma_f32_16x16x32_bf16 v[84:87], v[140:143], v[212:215], v[84:87]
	v_mfma_f32_16x16x32_bf16 v[76:79], v[148:151], v[212:215], v[76:79]
	v_mfma_f32_16x16x32_bf16 v[124:127], v[144:147], v[180:183], v[124:127]
	v_mfma_f32_16x16x32_bf16 v[120:123], v[152:155], v[180:183], v[120:123]
	v_mfma_f32_16x16x32_bf16 v[116:119], v[144:147], v[188:191], v[116:119]
	v_mfma_f32_16x16x32_bf16 v[108:111], v[152:155], v[188:191], v[108:111]
	v_mfma_f32_16x16x32_bf16 v[100:103], v[144:147], v[204:207], v[100:103]
	v_mfma_f32_16x16x32_bf16 v[92:95], v[152:155], v[204:207], v[92:95]
	v_mfma_f32_16x16x32_bf16 v[84:87], v[144:147], v[216:219], v[84:87]
	v_mfma_f32_16x16x32_bf16 v[76:79], v[152:155], v[216:219], v[76:79]
	v_mfma_f32_16x16x32_bf16 v[112:115], v[156:159], v[176:179], v[112:115]
	v_mfma_f32_16x16x32_bf16 v[104:107], v[168:171], v[176:179], v[104:107]
	v_mfma_f32_16x16x32_bf16 v[96:99], v[156:159], v[184:187], v[96:99]
	v_mfma_f32_16x16x32_bf16 v[88:91], v[168:171], v[184:187], v[88:91]
	v_mfma_f32_16x16x32_bf16 v[80:83], v[156:159], v[192:195], v[80:83]
	v_mfma_f32_16x16x32_bf16 v[72:75], v[168:171], v[192:195], v[72:75]
	v_mfma_f32_16x16x32_bf16 v[68:71], v[156:159], v[212:215], v[68:71]
	v_mfma_f32_16x16x32_bf16 v[64:67], v[168:171], v[212:215], v[64:67]
	v_mfma_f32_16x16x32_bf16 v[112:115], v[164:167], v[180:183], v[112:115]
	v_mfma_f32_16x16x32_bf16 v[104:107], v[172:175], v[180:183], v[104:107]
	v_mfma_f32_16x16x32_bf16 v[96:99], v[164:167], v[188:191], v[96:99]
	v_mfma_f32_16x16x32_bf16 v[88:91], v[172:175], v[188:191], v[88:91]
	v_mfma_f32_16x16x32_bf16 v[80:83], v[164:167], v[204:207], v[80:83]
	v_mfma_f32_16x16x32_bf16 v[72:75], v[172:175], v[204:207], v[72:75]
	v_mfma_f32_16x16x32_bf16 v[68:71], v[164:167], v[216:219], v[68:71]
	v_mfma_f32_16x16x32_bf16 v[64:67], v[172:175], v[216:219], v[64:67]
	s_barrier
	s_mov_b32 m0, s37
	v_lshl_add_u64 v[134:135], v[134:135], 0, s[10:11]
	ds_read_b128 v[176:179], v139 offset:49152
	ds_read_b128 v[180:183], v139 offset:50176
	ds_read_b128 v[184:187], v139 offset:51200
	ds_read_b128 v[188:191], v139 offset:52224
	ds_read_b128 v[192:195], v139 offset:53248
	ds_read_b128 v[204:207], v139 offset:54272
	ds_read_b128 v[212:215], v139 offset:55296
	ds_read_b128 v[216:219], v139 offset:56320
	global_load_lds_dwordx4 v[134:135], off
	v_lshl_add_u64 v[134:135], v[220:221], 0, s[10:11]
	s_mov_b32 m0, s36
	s_nop 0
	global_load_lds_dwordx4 v[134:135], off
	v_lshl_add_u64 v[134:135], s[50:51], 0, v[196:197]
	s_mov_b32 m0, s68
	s_nop 0
	global_load_lds_dwordx4 v[134:135], off
	v_lshl_add_u64 v[134:135], s[50:51], 0, v[132:133]
	s_mov_b32 m0, s67
	s_nop 0
	global_load_lds_dwordx4 v[134:135], off
	v_lshl_add_u64 v[134:135], v[222:223], 0, s[10:11]
	s_mov_b32 m0, s4
	s_nop 0
	global_load_lds_dwordx4 v[134:135], off
	v_lshl_add_u64 v[134:135], v[232:233], 0, s[10:11]
	s_mov_b32 m0, s28
	s_nop 0
	global_load_lds_dwordx4 v[134:135], off
	s_waitcnt vmcnt(8)
	s_waitcnt lgkmcnt(0)
	s_barrier
	s_waitcnt lgkmcnt(0)
	v_mfma_f32_16x16x32_bf16 v[60:63], v[140:143], v[176:179], v[60:63]
	v_mfma_f32_16x16x32_bf16 v[56:59], v[148:151], v[176:179], v[56:59]
	v_mfma_f32_16x16x32_bf16 v[52:55], v[140:143], v[184:187], v[52:55]
	v_mfma_f32_16x16x32_bf16 v[44:47], v[148:151], v[184:187], v[44:47]
	v_mfma_f32_16x16x32_bf16 v[36:39], v[140:143], v[192:195], v[36:39]
	v_mfma_f32_16x16x32_bf16 v[28:31], v[148:151], v[192:195], v[28:31]
	v_mfma_f32_16x16x32_bf16 v[20:23], v[140:143], v[212:215], v[20:23]
	v_mfma_f32_16x16x32_bf16 v[12:15], v[148:151], v[212:215], v[12:15]
	v_mfma_f32_16x16x32_bf16 v[60:63], v[144:147], v[180:183], v[60:63]
	v_mfma_f32_16x16x32_bf16 v[56:59], v[152:155], v[180:183], v[56:59]
	v_mfma_f32_16x16x32_bf16 v[52:55], v[144:147], v[188:191], v[52:55]
	v_mfma_f32_16x16x32_bf16 v[44:47], v[152:155], v[188:191], v[44:47]
	v_mfma_f32_16x16x32_bf16 v[36:39], v[144:147], v[204:207], v[36:39]
	v_mfma_f32_16x16x32_bf16 v[28:31], v[152:155], v[204:207], v[28:31]
	v_mfma_f32_16x16x32_bf16 v[20:23], v[144:147], v[216:219], v[20:23]
	v_mfma_f32_16x16x32_bf16 v[12:15], v[152:155], v[216:219], v[12:15]
	v_mfma_f32_16x16x32_bf16 v[48:51], v[156:159], v[176:179], v[48:51]
	v_mfma_f32_16x16x32_bf16 v[40:43], v[168:171], v[176:179], v[40:43]
	v_mfma_f32_16x16x32_bf16 v[32:35], v[156:159], v[184:187], v[32:35]
	v_mfma_f32_16x16x32_bf16 v[24:27], v[168:171], v[184:187], v[24:27]
	v_mfma_f32_16x16x32_bf16 v[16:19], v[156:159], v[192:195], v[16:19]
	v_mfma_f32_16x16x32_bf16 v[8:11], v[168:171], v[192:195], v[8:11]
	v_mfma_f32_16x16x32_bf16 v[4:7], v[156:159], v[212:215], v[4:7]
	v_mfma_f32_16x16x32_bf16 v[0:3], v[168:171], v[212:215], v[0:3]
	v_mfma_f32_16x16x32_bf16 v[48:51], v[164:167], v[180:183], v[48:51]
	v_mfma_f32_16x16x32_bf16 v[40:43], v[172:175], v[180:183], v[40:43]
	v_mfma_f32_16x16x32_bf16 v[32:35], v[164:167], v[188:191], v[32:35]
	v_mfma_f32_16x16x32_bf16 v[24:27], v[172:175], v[188:191], v[24:27]
	v_mfma_f32_16x16x32_bf16 v[16:19], v[164:167], v[204:207], v[16:19]
	v_mfma_f32_16x16x32_bf16 v[8:11], v[172:175], v[204:207], v[8:11]
	v_mfma_f32_16x16x32_bf16 v[4:7], v[164:167], v[216:219], v[4:7]
	v_mfma_f32_16x16x32_bf16 v[0:3], v[172:175], v[216:219], v[0:3]
	s_barrier
	s_movk_i32 s36, 0x100
	s_andn2_b64 vcc, exec, s[48:49]
	s_mov_b64 s[50:51], -1
	s_mov_b64 s[48:49], 0
	s_cbranch_vccz .LBB0_823
	s_and_b64 vcc, exec, s[12:13]
	s_cbranch_vccz .LBB0_826
	s_barrier

.LBB0_903:
	s_add_u32 s40, s18, 0x100
	s_addc_u32 s41, s19, 0
	s_add_i32 s48, 0, 0x10000
	s_cmp_eq_u32 s47, 40
	s_cselect_b32 s45, s15, s41
	s_cselect_b32 s44, s14, s40
	s_cselect_b32 s43, s17, s46
	s_cselect_b32 s42, s16, s37
	s_add_i32 s49, 0, 0x14000
	v_add_u32_e32 v154, s48, v143
	v_add_u32_e32 v158, s49, v143
	ds_read_b128 v[138:141], v154
	ds_read_b128 v[146:149], v154 offset:1024
	ds_read_b128 v[150:153], v154 offset:2048
	ds_read_b128 v[154:157], v154 offset:3072
	ds_read_b128 v[164:167], v158
	ds_read_b128 v[168:171], v158 offset:1024
	ds_read_b128 v[172:175], v158 offset:2048
	ds_read_b128 v[176:179], v158 offset:3072
	v_lshl_add_u64 v[158:159], s[18:19], 0, v[134:135]
	s_add_i32 m0, s23, 0xc000
	ds_read_b128 v[180:183], v145
	ds_read_b128 v[184:187], v145 offset:1024
	ds_read_b128 v[188:191], v145 offset:2048
	ds_read_b128 v[192:195], v145 offset:3072
	ds_read_b128 v[204:207], v145 offset:4096
	ds_read_b128 v[212:215], v145 offset:5120
	ds_read_b128 v[216:219], v145 offset:6144
	ds_read_b128 v[220:223], v145 offset:7168
	global_load_lds_dwordx4 v[158:159], off
	v_lshl_add_u64 v[158:159], s[18:19], 0, v[136:137]
	s_add_i32 m0, s23, 0xe000
	s_nop 0
	global_load_lds_dwordx4 v[158:159], off
	s_waitcnt vmcnt(8)
	s_waitcnt lgkmcnt(0)
	s_barrier
	s_waitcnt lgkmcnt(0)
	v_mfma_f32_16x16x32_bf16 v[124:127], v[138:141], v[180:183], v[124:127]
	v_mfma_f32_16x16x32_bf16 v[120:123], v[150:153], v[180:183], v[120:123]
	v_mfma_f32_16x16x32_bf16 v[112:115], v[138:141], v[188:191], v[112:115]
	v_mfma_f32_16x16x32_bf16 v[104:107], v[150:153], v[188:191], v[104:107]
	v_mfma_f32_16x16x32_bf16 v[96:99], v[138:141], v[204:207], v[96:99]
	v_mfma_f32_16x16x32_bf16 v[88:91], v[150:153], v[204:207], v[88:91]
	v_mfma_f32_16x16x32_bf16 v[80:83], v[138:141], v[216:219], v[80:83]
	v_mfma_f32_16x16x32_bf16 v[72:75], v[150:153], v[216:219], v[72:75]
	v_mfma_f32_16x16x32_bf16 v[124:127], v[146:149], v[184:187], v[124:127]
	v_mfma_f32_16x16x32_bf16 v[120:123], v[154:157], v[184:187], v[120:123]
	v_mfma_f32_16x16x32_bf16 v[112:115], v[146:149], v[192:195], v[112:115]
	v_mfma_f32_16x16x32_bf16 v[104:107], v[154:157], v[192:195], v[104:107]
	v_mfma_f32_16x16x32_bf16 v[96:99], v[146:149], v[212:215], v[96:99]
	v_mfma_f32_16x16x32_bf16 v[88:91], v[154:157], v[212:215], v[88:91]
	v_mfma_f32_16x16x32_bf16 v[80:83], v[146:149], v[220:223], v[80:83]
	v_mfma_f32_16x16x32_bf16 v[72:75], v[154:157], v[220:223], v[72:75]
	v_mfma_f32_16x16x32_bf16 v[116:119], v[164:167], v[180:183], v[116:119]
	v_mfma_f32_16x16x32_bf16 v[108:111], v[172:175], v[180:183], v[108:111]
	v_mfma_f32_16x16x32_bf16 v[100:103], v[164:167], v[188:191], v[100:103]
	v_mfma_f32_16x16x32_bf16 v[92:95], v[172:175], v[188:191], v[92:95]
	v_mfma_f32_16x16x32_bf16 v[84:87], v[164:167], v[204:207], v[84:87]
	v_mfma_f32_16x16x32_bf16 v[76:79], v[172:175], v[204:207], v[76:79]
	v_mfma_f32_16x16x32_bf16 v[68:71], v[164:167], v[216:219], v[68:71]
	v_mfma_f32_16x16x32_bf16 v[64:67], v[172:175], v[216:219], v[64:67]
	v_mfma_f32_16x16x32_bf16 v[116:119], v[168:171], v[184:187], v[116:119]
	v_mfma_f32_16x16x32_bf16 v[108:111], v[176:179], v[184:187], v[108:111]
	v_mfma_f32_16x16x32_bf16 v[100:103], v[168:171], v[192:195], v[100:103]
	v_mfma_f32_16x16x32_bf16 v[92:95], v[176:179], v[192:195], v[92:95]
	v_mfma_f32_16x16x32_bf16 v[84:87], v[168:171], v[212:215], v[84:87]
	v_mfma_f32_16x16x32_bf16 v[76:79], v[176:179], v[212:215], v[76:79]
	v_mfma_f32_16x16x32_bf16 v[68:71], v[168:171], v[220:223], v[68:71]
	v_mfma_f32_16x16x32_bf16 v[64:67], v[176:179], v[220:223], v[64:67]
	s_barrier
	s_add_i32 s18, s48, s22
	v_lshl_add_u64 v[158:159], s[42:43], 0, v[196:197]
	s_mov_b32 m0, s18
	ds_read_b128 v[180:183], v145 offset:16384
	ds_read_b128 v[184:187], v145 offset:17408
	ds_read_b128 v[188:191], v145 offset:18432
	ds_read_b128 v[192:195], v145 offset:19456
	ds_read_b128 v[204:207], v145 offset:20480
	ds_read_b128 v[212:215], v145 offset:21504
	ds_read_b128 v[216:219], v145 offset:22528
	ds_read_b128 v[220:223], v145 offset:23552
	global_load_lds_dwordx4 v[158:159], off
	s_add_i32 m0, s18, 0x2000
	s_add_u32 s18, s42, 0xb0000
	v_lshl_add_u64 v[232:233], s[42:43], 0, v[132:133]
	s_addc_u32 s19, s43, 0
	s_add_i32 s48, s49, s22
	global_load_lds_dwordx4 v[232:233], off
	v_lshl_add_u64 v[234:235], s[18:19], 0, v[196:197]
	s_mov_b32 m0, s48
	v_lshl_add_u64 v[236:237], s[44:45], 0, v[130:131]
	global_load_lds_dwordx4 v[234:235], off
	v_lshl_add_u64 v[234:235], s[18:19], 0, v[132:133]
	s_add_i32 m0, s48, 0x2000
	s_nop 0
	global_load_lds_dwordx4 v[234:235], off
	v_lshl_add_u64 v[234:235], s[44:45], 0, v[128:129]
	s_mov_b32 m0, s23
	s_nop 0
	global_load_lds_dwordx4 v[234:235], off
	s_mov_b32 m0, s24
	s_nop 0
	global_load_lds_dwordx4 v[236:237], off
	s_waitcnt vmcnt(8)
	s_waitcnt lgkmcnt(0)
	s_barrier
	s_waitcnt lgkmcnt(0)
	v_mfma_f32_16x16x32_bf16 v[60:63], v[138:141], v[180:183], v[60:63]
	v_mfma_f32_16x16x32_bf16 v[56:59], v[150:153], v[180:183], v[56:59]
	v_mfma_f32_16x16x32_bf16 v[48:51], v[138:141], v[188:191], v[48:51]
	v_mfma_f32_16x16x32_bf16 v[40:43], v[150:153], v[188:191], v[40:43]
	v_mfma_f32_16x16x32_bf16 v[32:35], v[138:141], v[204:207], v[32:35]
	v_mfma_f32_16x16x32_bf16 v[24:27], v[150:153], v[204:207], v[24:27]
	v_mfma_f32_16x16x32_bf16 v[16:19], v[138:141], v[216:219], v[16:19]
	v_mfma_f32_16x16x32_bf16 v[8:11], v[150:153], v[216:219], v[8:11]
	v_mfma_f32_16x16x32_bf16 v[60:63], v[146:149], v[184:187], v[60:63]
	v_mfma_f32_16x16x32_bf16 v[56:59], v[154:157], v[184:187], v[56:59]
	v_mfma_f32_16x16x32_bf16 v[48:51], v[146:149], v[192:195], v[48:51]
	v_mfma_f32_16x16x32_bf16 v[40:43], v[154:157], v[192:195], v[40:43]
	v_mfma_f32_16x16x32_bf16 v[32:35], v[146:149], v[212:215], v[32:35]
	v_mfma_f32_16x16x32_bf16 v[24:27], v[154:157], v[212:215], v[24:27]
	v_mfma_f32_16x16x32_bf16 v[16:19], v[146:149], v[220:223], v[16:19]
	v_mfma_f32_16x16x32_bf16 v[8:11], v[154:157], v[220:223], v[8:11]
	v_mfma_f32_16x16x32_bf16 v[52:55], v[164:167], v[180:183], v[52:55]
	v_mfma_f32_16x16x32_bf16 v[44:47], v[172:175], v[180:183], v[44:47]
	v_mfma_f32_16x16x32_bf16 v[36:39], v[164:167], v[188:191], v[36:39]
	v_mfma_f32_16x16x32_bf16 v[28:31], v[172:175], v[188:191], v[28:31]
	v_mfma_f32_16x16x32_bf16 v[20:23], v[164:167], v[204:207], v[20:23]
	v_mfma_f32_16x16x32_bf16 v[12:15], v[172:175], v[204:207], v[12:15]
	v_mfma_f32_16x16x32_bf16 v[4:7], v[164:167], v[216:219], v[4:7]
	v_mfma_f32_16x16x32_bf16 v[0:3], v[172:175], v[216:219], v[0:3]
	v_mfma_f32_16x16x32_bf16 v[52:55], v[168:171], v[184:187], v[52:55]
	v_mfma_f32_16x16x32_bf16 v[44:47], v[176:179], v[184:187], v[44:47]
	v_mfma_f32_16x16x32_bf16 v[36:39], v[168:171], v[192:195], v[36:39]
	v_mfma_f32_16x16x32_bf16 v[28:31], v[176:179], v[192:195], v[28:31]
	v_mfma_f32_16x16x32_bf16 v[20:23], v[168:171], v[212:215], v[20:23]
	v_mfma_f32_16x16x32_bf16 v[12:15], v[176:179], v[212:215], v[12:15]
	v_mfma_f32_16x16x32_bf16 v[4:7], v[168:171], v[220:223], v[4:7]
	v_mfma_f32_16x16x32_bf16 v[0:3], v[176:179], v[220:223], v[0:3]
	s_barrier
	s_add_i32 s48, 0, 0x18000
	s_add_i32 s49, 0, 0x1c000
	v_add_u32_e32 v154, s48, v143
	v_add_u32_e32 v176, s49, v143
	ds_read_b128 v[138:141], v154
	ds_read_b128 v[146:149], v154 offset:1024
	ds_read_b128 v[150:153], v154 offset:2048
	ds_read_b128 v[154:157], v154 offset:3072
	ds_read_b128 v[164:167], v176
	ds_read_b128 v[168:171], v176 offset:1024
	ds_read_b128 v[172:175], v176 offset:2048
	ds_read_b128 v[176:179], v176 offset:3072
	s_add_u32 s18, s44, 0xb0000
	s_addc_u32 s19, s45, 0
	s_mov_b32 m0, s25
	v_lshl_add_u64 v[238:239], s[18:19], 0, v[128:129]
	ds_read_b128 v[180:183], v145 offset:32768
	ds_read_b128 v[184:187], v145 offset:33792
	ds_read_b128 v[188:191], v145 offset:34816
	ds_read_b128 v[192:195], v145 offset:35840
	ds_read_b128 v[204:207], v145 offset:36864
	ds_read_b128 v[212:215], v145 offset:37888
	ds_read_b128 v[216:219], v145 offset:38912
	ds_read_b128 v[220:223], v145 offset:39936
	global_load_lds_dwordx4 v[238:239], off
	v_lshl_add_u64 v[238:239], s[18:19], 0, v[130:131]
	s_mov_b32 m0, s26
	s_nop 0
	global_load_lds_dwordx4 v[238:239], off
	s_waitcnt vmcnt(8)
	s_waitcnt lgkmcnt(0)
	s_barrier
	s_waitcnt lgkmcnt(0)
	v_mfma_f32_16x16x32_bf16 v[124:127], v[138:141], v[180:183], v[124:127]
	v_mfma_f32_16x16x32_bf16 v[120:123], v[150:153], v[180:183], v[120:123]
	v_mfma_f32_16x16x32_bf16 v[112:115], v[138:141], v[188:191], v[112:115]
	v_mfma_f32_16x16x32_bf16 v[104:107], v[150:153], v[188:191], v[104:107]
	v_mfma_f32_16x16x32_bf16 v[96:99], v[138:141], v[204:207], v[96:99]
	v_mfma_f32_16x16x32_bf16 v[88:91], v[150:153], v[204:207], v[88:91]
	v_mfma_f32_16x16x32_bf16 v[80:83], v[138:141], v[216:219], v[80:83]
	v_mfma_f32_16x16x32_bf16 v[72:75], v[150:153], v[216:219], v[72:75]
	v_mfma_f32_16x16x32_bf16 v[124:127], v[146:149], v[184:187], v[124:127]
	v_mfma_f32_16x16x32_bf16 v[120:123], v[154:157], v[184:187], v[120:123]
	v_mfma_f32_16x16x32_bf16 v[112:115], v[146:149], v[192:195], v[112:115]
	v_mfma_f32_16x16x32_bf16 v[104:107], v[154:157], v[192:195], v[104:107]
	v_mfma_f32_16x16x32_bf16 v[96:99], v[146:149], v[212:215], v[96:99]
	v_mfma_f32_16x16x32_bf16 v[88:91], v[154:157], v[212:215], v[88:91]
	v_mfma_f32_16x16x32_bf16 v[80:83], v[146:149], v[220:223], v[80:83]
	v_mfma_f32_16x16x32_bf16 v[72:75], v[154:157], v[220:223], v[72:75]
	v_mfma_f32_16x16x32_bf16 v[116:119], v[164:167], v[180:183], v[116:119]
	v_mfma_f32_16x16x32_bf16 v[108:111], v[172:175], v[180:183], v[108:111]
	v_mfma_f32_16x16x32_bf16 v[100:103], v[164:167], v[188:191], v[100:103]
	v_mfma_f32_16x16x32_bf16 v[92:95], v[172:175], v[188:191], v[92:95]
	v_mfma_f32_16x16x32_bf16 v[84:87], v[164:167], v[204:207], v[84:87]
	v_mfma_f32_16x16x32_bf16 v[76:79], v[172:175], v[204:207], v[76:79]
	v_mfma_f32_16x16x32_bf16 v[68:71], v[164:167], v[216:219], v[68:71]
	v_mfma_f32_16x16x32_bf16 v[64:67], v[172:175], v[216:219], v[64:67]
	v_mfma_f32_16x16x32_bf16 v[116:119], v[168:171], v[184:187], v[116:119]
	v_mfma_f32_16x16x32_bf16 v[108:111], v[176:179], v[184:187], v[108:111]
	v_mfma_f32_16x16x32_bf16 v[100:103], v[168:171], v[192:195], v[100:103]
	v_mfma_f32_16x16x32_bf16 v[92:95], v[176:179], v[192:195], v[92:95]
	v_mfma_f32_16x16x32_bf16 v[84:87], v[168:171], v[212:215], v[84:87]
	v_mfma_f32_16x16x32_bf16 v[76:79], v[176:179], v[212:215], v[76:79]
	v_mfma_f32_16x16x32_bf16 v[68:71], v[168:171], v[220:223], v[68:71]
	v_mfma_f32_16x16x32_bf16 v[64:67], v[176:179], v[220:223], v[64:67]
	s_barrier
	s_add_i32 s18, s48, s22
	v_lshl_add_u64 v[158:159], v[158:159], 0, s[10:11]
	s_mov_b32 m0, s18
	ds_read_b128 v[180:183], v145 offset:49152
	ds_read_b128 v[184:187], v145 offset:50176
	ds_read_b128 v[188:191], v145 offset:51200
	ds_read_b128 v[192:195], v145 offset:52224
	ds_read_b128 v[204:207], v145 offset:53248
	ds_read_b128 v[212:215], v145 offset:54272
	ds_read_b128 v[216:219], v145 offset:55296
	ds_read_b128 v[220:223], v145 offset:56320
	global_load_lds_dwordx4 v[158:159], off
	s_add_i32 m0, s18, 0x2000
	s_add_u32 s18, s42, 0xb0080
	v_lshl_add_u64 v[158:159], v[232:233], 0, s[10:11]
	s_addc_u32 s19, s43, 0
	s_add_i32 s42, s49, s22
	global_load_lds_dwordx4 v[158:159], off
	v_lshl_add_u64 v[158:159], s[18:19], 0, v[196:197]
	s_mov_b32 m0, s42
	s_nop 0
	global_load_lds_dwordx4 v[158:159], off
	v_lshl_add_u64 v[158:159], s[18:19], 0, v[132:133]
	s_add_i32 m0, s42, 0x2000
	s_nop 0
	global_load_lds_dwordx4 v[158:159], off
	v_lshl_add_u64 v[158:159], v[234:235], 0, s[10:11]
	s_mov_b32 m0, s27
	s_nop 0
	global_load_lds_dwordx4 v[158:159], off
	v_lshl_add_u64 v[158:159], v[236:237], 0, s[10:11]
	s_mov_b32 m0, s28
	s_nop 0
	global_load_lds_dwordx4 v[158:159], off
	s_waitcnt vmcnt(8)
	s_waitcnt lgkmcnt(0)
	s_barrier
	s_waitcnt lgkmcnt(0)
	v_mfma_f32_16x16x32_bf16 v[60:63], v[138:141], v[180:183], v[60:63]
	v_mfma_f32_16x16x32_bf16 v[56:59], v[150:153], v[180:183], v[56:59]
	v_mfma_f32_16x16x32_bf16 v[48:51], v[138:141], v[188:191], v[48:51]
	v_mfma_f32_16x16x32_bf16 v[40:43], v[150:153], v[188:191], v[40:43]
	v_mfma_f32_16x16x32_bf16 v[32:35], v[138:141], v[204:207], v[32:35]
	v_mfma_f32_16x16x32_bf16 v[24:27], v[150:153], v[204:207], v[24:27]
	v_mfma_f32_16x16x32_bf16 v[16:19], v[138:141], v[216:219], v[16:19]
	v_mfma_f32_16x16x32_bf16 v[8:11], v[150:153], v[216:219], v[8:11]
	v_mfma_f32_16x16x32_bf16 v[60:63], v[146:149], v[184:187], v[60:63]
	v_mfma_f32_16x16x32_bf16 v[56:59], v[154:157], v[184:187], v[56:59]
	v_mfma_f32_16x16x32_bf16 v[48:51], v[146:149], v[192:195], v[48:51]
	v_mfma_f32_16x16x32_bf16 v[40:43], v[154:157], v[192:195], v[40:43]
	v_mfma_f32_16x16x32_bf16 v[32:35], v[146:149], v[212:215], v[32:35]
	v_mfma_f32_16x16x32_bf16 v[24:27], v[154:157], v[212:215], v[24:27]
	v_mfma_f32_16x16x32_bf16 v[16:19], v[146:149], v[220:223], v[16:19]
	v_mfma_f32_16x16x32_bf16 v[8:11], v[154:157], v[220:223], v[8:11]
	v_mfma_f32_16x16x32_bf16 v[52:55], v[164:167], v[180:183], v[52:55]
	v_mfma_f32_16x16x32_bf16 v[44:47], v[172:175], v[180:183], v[44:47]
	v_mfma_f32_16x16x32_bf16 v[36:39], v[164:167], v[188:191], v[36:39]
	v_mfma_f32_16x16x32_bf16 v[28:31], v[172:175], v[188:191], v[28:31]
	v_mfma_f32_16x16x32_bf16 v[20:23], v[164:167], v[204:207], v[20:23]
	v_mfma_f32_16x16x32_bf16 v[12:15], v[172:175], v[204:207], v[12:15]
	v_mfma_f32_16x16x32_bf16 v[4:7], v[164:167], v[216:219], v[4:7]
	v_mfma_f32_16x16x32_bf16 v[0:3], v[172:175], v[216:219], v[0:3]
	v_mfma_f32_16x16x32_bf16 v[52:55], v[168:171], v[184:187], v[52:55]
	v_mfma_f32_16x16x32_bf16 v[44:47], v[176:179], v[184:187], v[44:47]
	v_mfma_f32_16x16x32_bf16 v[36:39], v[168:171], v[192:195], v[36:39]
	v_mfma_f32_16x16x32_bf16 v[28:31], v[176:179], v[192:195], v[28:31]
	v_mfma_f32_16x16x32_bf16 v[20:23], v[168:171], v[212:215], v[20:23]
	v_mfma_f32_16x16x32_bf16 v[12:15], v[176:179], v[212:215], v[12:15]
	v_mfma_f32_16x16x32_bf16 v[4:7], v[168:171], v[220:223], v[4:7]
	v_mfma_f32_16x16x32_bf16 v[0:3], v[176:179], v[220:223], v[0:3]
	s_barrier
	s_add_i32 s47, s47, 2
	s_add_u32 s37, s37, 0x100
	s_addc_u32 s46, s46, 0
	s_cmp_gt_u32 s47, 41
	s_mov_b64 s[18:19], s[40:41]
	s_cbranch_scc0 .LBB0_903
	s_and_b64 vcc, exec, s[12:13]
	s_cbranch_vccz .LBB0_906
	s_barrier

.LBB0_978:
	s_add_u32 s31, s6, s48
	s_addc_u32 s34, s7, s49
	s_add_u32 s31, s31, 0x100
	s_addc_u32 s34, s34, 0
	s_add_u32 s35, s26, s48
	s_addc_u32 s36, s27, s49
	s_add_i32 s37, 0, 0x10000
	s_cmpk_eq_i32 s48, 0x700
	s_cselect_b32 s53, s13, s34
	s_cselect_b32 s52, s28, s31
	v_add_u32_e32 v145, s37, v143
	s_cselect_b32 s51, s9, s36
	s_cselect_b32 s50, s29, s35
	s_add_i32 s31, 0, 0x14000
	ds_read_b128 v[146:149], v145
	ds_read_b128 v[150:153], v145 offset:1024
	ds_read_b128 v[156:159], v145 offset:2048
	ds_read_b128 v[164:167], v145 offset:3072
	v_add_u32_e32 v145, s31, v143
	ds_read_b128 v[168:171], v145
	ds_read_b128 v[172:175], v145 offset:1024
	ds_read_b128 v[176:179], v145 offset:2048
	ds_read_b128 v[180:183], v145 offset:3072
	v_lshl_add_u64 v[236:237], v[138:139], 0, s[48:49]
	s_add_i32 m0, s2, 0xc000
	ds_read_b128 v[184:187], v144
	ds_read_b128 v[188:191], v144 offset:1024
	ds_read_b128 v[192:195], v144 offset:2048
	ds_read_b128 v[204:207], v144 offset:3072
	ds_read_b128 v[212:215], v144 offset:4096
	ds_read_b128 v[216:219], v144 offset:5120
	ds_read_b128 v[220:223], v144 offset:6144
	ds_read_b128 v[232:235], v144 offset:7168
	global_load_lds_dwordx4 v[236:237], off
	v_lshl_add_u64 v[236:237], v[140:141], 0, s[48:49]
	s_add_i32 m0, s2, 0xe000
	s_nop 0
	global_load_lds_dwordx4 v[236:237], off
	s_waitcnt vmcnt(8)
	s_waitcnt lgkmcnt(0)
	s_barrier
	s_waitcnt lgkmcnt(0)
	v_mfma_f32_16x16x32_bf16 v[124:127], v[146:149], v[184:187], v[124:127]
	v_mfma_f32_16x16x32_bf16 v[120:123], v[156:159], v[184:187], v[120:123]
	v_mfma_f32_16x16x32_bf16 v[108:111], v[146:149], v[192:195], v[108:111]
	v_mfma_f32_16x16x32_bf16 v[104:107], v[156:159], v[192:195], v[104:107]
	v_mfma_f32_16x16x32_bf16 v[92:95], v[146:149], v[212:215], v[92:95]
	v_mfma_f32_16x16x32_bf16 v[88:91], v[156:159], v[212:215], v[88:91]
	v_mfma_f32_16x16x32_bf16 v[76:79], v[146:149], v[220:223], v[76:79]
	v_mfma_f32_16x16x32_bf16 v[72:75], v[156:159], v[220:223], v[72:75]
	v_mfma_f32_16x16x32_bf16 v[124:127], v[150:153], v[188:191], v[124:127]
	v_mfma_f32_16x16x32_bf16 v[120:123], v[164:167], v[188:191], v[120:123]
	v_mfma_f32_16x16x32_bf16 v[108:111], v[150:153], v[204:207], v[108:111]
	v_mfma_f32_16x16x32_bf16 v[104:107], v[164:167], v[204:207], v[104:107]
	v_mfma_f32_16x16x32_bf16 v[92:95], v[150:153], v[216:219], v[92:95]
	v_mfma_f32_16x16x32_bf16 v[88:91], v[164:167], v[216:219], v[88:91]
	v_mfma_f32_16x16x32_bf16 v[76:79], v[150:153], v[232:235], v[76:79]
	v_mfma_f32_16x16x32_bf16 v[72:75], v[164:167], v[232:235], v[72:75]
	v_mfma_f32_16x16x32_bf16 v[116:119], v[168:171], v[184:187], v[116:119]
	v_mfma_f32_16x16x32_bf16 v[112:115], v[176:179], v[184:187], v[112:115]
	v_mfma_f32_16x16x32_bf16 v[100:103], v[168:171], v[192:195], v[100:103]
	v_mfma_f32_16x16x32_bf16 v[96:99], v[176:179], v[192:195], v[96:99]
	v_mfma_f32_16x16x32_bf16 v[84:87], v[168:171], v[212:215], v[84:87]
	v_mfma_f32_16x16x32_bf16 v[80:83], v[176:179], v[212:215], v[80:83]
	v_mfma_f32_16x16x32_bf16 v[68:71], v[168:171], v[220:223], v[68:71]
	v_mfma_f32_16x16x32_bf16 v[64:67], v[176:179], v[220:223], v[64:67]
	v_mfma_f32_16x16x32_bf16 v[116:119], v[172:175], v[188:191], v[116:119]
	v_mfma_f32_16x16x32_bf16 v[112:115], v[180:183], v[188:191], v[112:115]
	v_mfma_f32_16x16x32_bf16 v[100:103], v[172:175], v[204:207], v[100:103]
	v_mfma_f32_16x16x32_bf16 v[96:99], v[180:183], v[204:207], v[96:99]
	v_mfma_f32_16x16x32_bf16 v[84:87], v[172:175], v[216:219], v[84:87]
	v_mfma_f32_16x16x32_bf16 v[80:83], v[180:183], v[216:219], v[80:83]
	v_mfma_f32_16x16x32_bf16 v[68:71], v[172:175], v[232:235], v[68:71]
	v_mfma_f32_16x16x32_bf16 v[64:67], v[180:183], v[232:235], v[64:67]
	s_barrier
	s_add_i32 s34, s37, s1
	v_lshl_add_u64 v[236:237], s[50:51], 0, v[196:197]
	s_mov_b32 m0, s34
	ds_read_b128 v[184:187], v144 offset:16384
	ds_read_b128 v[188:191], v144 offset:17408
	ds_read_b128 v[192:195], v144 offset:18432
	ds_read_b128 v[204:207], v144 offset:19456
	ds_read_b128 v[212:215], v144 offset:20480
	ds_read_b128 v[216:219], v144 offset:21504
	ds_read_b128 v[220:223], v144 offset:22528
	ds_read_b128 v[232:235], v144 offset:23552
	global_load_lds_dwordx4 v[236:237], off
	s_add_i32 m0, s34, 0x2000
	s_add_u32 s34, s50, 0x40000
	v_lshl_add_u64 v[238:239], s[50:51], 0, v[132:133]
	s_addc_u32 s35, s51, 0
	s_add_i32 s31, s31, s1
	global_load_lds_dwordx4 v[238:239], off
	v_lshl_add_u64 v[240:241], s[34:35], 0, v[196:197]
	s_mov_b32 m0, s31
	v_lshl_add_u64 v[242:243], s[52:53], 0, v[130:131]
	global_load_lds_dwordx4 v[240:241], off
	v_lshl_add_u64 v[240:241], s[34:35], 0, v[132:133]
	s_add_i32 m0, s31, 0x2000
	s_nop 0
	global_load_lds_dwordx4 v[240:241], off
	v_lshl_add_u64 v[240:241], s[52:53], 0, v[128:129]
	s_mov_b32 m0, s2
	s_nop 0
	global_load_lds_dwordx4 v[240:241], off
	s_mov_b32 m0, s19
	s_nop 0
	global_load_lds_dwordx4 v[242:243], off
	s_waitcnt vmcnt(8)
	s_waitcnt lgkmcnt(0)
	s_barrier
	s_waitcnt lgkmcnt(0)
	v_mfma_f32_16x16x32_bf16 v[60:63], v[146:149], v[184:187], v[60:63]
	v_mfma_f32_16x16x32_bf16 v[56:59], v[156:159], v[184:187], v[56:59]
	v_mfma_f32_16x16x32_bf16 v[44:47], v[146:149], v[192:195], v[44:47]
	v_mfma_f32_16x16x32_bf16 v[40:43], v[156:159], v[192:195], v[40:43]
	v_mfma_f32_16x16x32_bf16 v[28:31], v[146:149], v[212:215], v[28:31]
	v_mfma_f32_16x16x32_bf16 v[24:27], v[156:159], v[212:215], v[24:27]
	v_mfma_f32_16x16x32_bf16 v[12:15], v[146:149], v[220:223], v[12:15]
	v_mfma_f32_16x16x32_bf16 v[8:11], v[156:159], v[220:223], v[8:11]
	v_mfma_f32_16x16x32_bf16 v[60:63], v[150:153], v[188:191], v[60:63]
	v_mfma_f32_16x16x32_bf16 v[56:59], v[164:167], v[188:191], v[56:59]
	v_mfma_f32_16x16x32_bf16 v[44:47], v[150:153], v[204:207], v[44:47]
	v_mfma_f32_16x16x32_bf16 v[40:43], v[164:167], v[204:207], v[40:43]
	v_mfma_f32_16x16x32_bf16 v[28:31], v[150:153], v[216:219], v[28:31]
	v_mfma_f32_16x16x32_bf16 v[24:27], v[164:167], v[216:219], v[24:27]
	v_mfma_f32_16x16x32_bf16 v[12:15], v[150:153], v[232:235], v[12:15]
	v_mfma_f32_16x16x32_bf16 v[8:11], v[164:167], v[232:235], v[8:11]
	v_mfma_f32_16x16x32_bf16 v[52:55], v[168:171], v[184:187], v[52:55]
	v_mfma_f32_16x16x32_bf16 v[48:51], v[176:179], v[184:187], v[48:51]
	v_mfma_f32_16x16x32_bf16 v[36:39], v[168:171], v[192:195], v[36:39]
	v_mfma_f32_16x16x32_bf16 v[32:35], v[176:179], v[192:195], v[32:35]
	v_mfma_f32_16x16x32_bf16 v[20:23], v[168:171], v[212:215], v[20:23]
	v_mfma_f32_16x16x32_bf16 v[16:19], v[176:179], v[212:215], v[16:19]
	v_mfma_f32_16x16x32_bf16 v[4:7], v[168:171], v[220:223], v[4:7]
	v_mfma_f32_16x16x32_bf16 v[0:3], v[176:179], v[220:223], v[0:3]
	v_mfma_f32_16x16x32_bf16 v[52:55], v[172:175], v[188:191], v[52:55]
	v_mfma_f32_16x16x32_bf16 v[48:51], v[180:183], v[188:191], v[48:51]
	v_mfma_f32_16x16x32_bf16 v[36:39], v[172:175], v[204:207], v[36:39]
	v_mfma_f32_16x16x32_bf16 v[32:35], v[180:183], v[204:207], v[32:35]
	v_mfma_f32_16x16x32_bf16 v[20:23], v[172:175], v[216:219], v[20:23]
	v_mfma_f32_16x16x32_bf16 v[16:19], v[180:183], v[216:219], v[16:19]
	v_mfma_f32_16x16x32_bf16 v[4:7], v[172:175], v[232:235], v[4:7]
	v_mfma_f32_16x16x32_bf16 v[0:3], v[180:183], v[232:235], v[0:3]
	s_barrier
	s_add_i32 s31, 0, 0x18000
	v_add_u32_e32 v145, s31, v143
	s_add_i32 s36, 0, 0x1c000
	ds_read_b128 v[146:149], v145
	ds_read_b128 v[150:153], v145 offset:1024
	ds_read_b128 v[156:159], v145 offset:2048
	ds_read_b128 v[164:167], v145 offset:3072
	v_add_u32_e32 v145, s36, v143
	ds_read_b128 v[168:171], v145
	ds_read_b128 v[172:175], v145 offset:1024
	ds_read_b128 v[176:179], v145 offset:2048
	ds_read_b128 v[180:183], v145 offset:3072
	s_add_u32 s34, s52, 0x40000
	s_addc_u32 s35, s53, 0
	s_mov_b32 m0, s20
	v_lshl_add_u64 v[244:245], s[34:35], 0, v[128:129]
	ds_read_b128 v[184:187], v144 offset:32768
	ds_read_b128 v[188:191], v144 offset:33792
	ds_read_b128 v[192:195], v144 offset:34816
	ds_read_b128 v[204:207], v144 offset:35840
	ds_read_b128 v[212:215], v144 offset:36864
	ds_read_b128 v[216:219], v144 offset:37888
	ds_read_b128 v[220:223], v144 offset:38912
	ds_read_b128 v[232:235], v144 offset:39936
	global_load_lds_dwordx4 v[244:245], off
	v_lshl_add_u64 v[244:245], s[34:35], 0, v[130:131]
	s_mov_b32 m0, s21
	s_nop 0
	global_load_lds_dwordx4 v[244:245], off
	s_waitcnt vmcnt(8)
	s_waitcnt lgkmcnt(0)
	s_barrier
	s_waitcnt lgkmcnt(0)
	v_mfma_f32_16x16x32_bf16 v[124:127], v[146:149], v[184:187], v[124:127]
	v_mfma_f32_16x16x32_bf16 v[120:123], v[156:159], v[184:187], v[120:123]
	v_mfma_f32_16x16x32_bf16 v[108:111], v[146:149], v[192:195], v[108:111]
	v_mfma_f32_16x16x32_bf16 v[104:107], v[156:159], v[192:195], v[104:107]
	v_mfma_f32_16x16x32_bf16 v[92:95], v[146:149], v[212:215], v[92:95]
	v_mfma_f32_16x16x32_bf16 v[88:91], v[156:159], v[212:215], v[88:91]
	v_mfma_f32_16x16x32_bf16 v[76:79], v[146:149], v[220:223], v[76:79]
	v_mfma_f32_16x16x32_bf16 v[72:75], v[156:159], v[220:223], v[72:75]
	v_mfma_f32_16x16x32_bf16 v[124:127], v[150:153], v[188:191], v[124:127]
	v_mfma_f32_16x16x32_bf16 v[120:123], v[164:167], v[188:191], v[120:123]
	v_mfma_f32_16x16x32_bf16 v[108:111], v[150:153], v[204:207], v[108:111]
	v_mfma_f32_16x16x32_bf16 v[104:107], v[164:167], v[204:207], v[104:107]
	v_mfma_f32_16x16x32_bf16 v[92:95], v[150:153], v[216:219], v[92:95]
	v_mfma_f32_16x16x32_bf16 v[88:91], v[164:167], v[216:219], v[88:91]
	v_mfma_f32_16x16x32_bf16 v[76:79], v[150:153], v[232:235], v[76:79]
	v_mfma_f32_16x16x32_bf16 v[72:75], v[164:167], v[232:235], v[72:75]
	v_mfma_f32_16x16x32_bf16 v[116:119], v[168:171], v[184:187], v[116:119]
	v_mfma_f32_16x16x32_bf16 v[112:115], v[176:179], v[184:187], v[112:115]
	v_mfma_f32_16x16x32_bf16 v[100:103], v[168:171], v[192:195], v[100:103]
	v_mfma_f32_16x16x32_bf16 v[96:99], v[176:179], v[192:195], v[96:99]
	v_mfma_f32_16x16x32_bf16 v[84:87], v[168:171], v[212:215], v[84:87]
	v_mfma_f32_16x16x32_bf16 v[80:83], v[176:179], v[212:215], v[80:83]
	v_mfma_f32_16x16x32_bf16 v[68:71], v[168:171], v[220:223], v[68:71]
	v_mfma_f32_16x16x32_bf16 v[64:67], v[176:179], v[220:223], v[64:67]
	v_mfma_f32_16x16x32_bf16 v[116:119], v[172:175], v[188:191], v[116:119]
	v_mfma_f32_16x16x32_bf16 v[112:115], v[180:183], v[188:191], v[112:115]
	v_mfma_f32_16x16x32_bf16 v[100:103], v[172:175], v[204:207], v[100:103]
	v_mfma_f32_16x16x32_bf16 v[96:99], v[180:183], v[204:207], v[96:99]
	v_mfma_f32_16x16x32_bf16 v[84:87], v[172:175], v[216:219], v[84:87]
	v_mfma_f32_16x16x32_bf16 v[80:83], v[180:183], v[216:219], v[80:83]
	v_mfma_f32_16x16x32_bf16 v[68:71], v[172:175], v[232:235], v[68:71]
	v_mfma_f32_16x16x32_bf16 v[64:67], v[180:183], v[232:235], v[64:67]
	s_barrier
	s_add_i32 s31, s31, s1
	v_lshl_add_u64 v[236:237], v[236:237], 0, s[10:11]
	s_mov_b32 m0, s31
	ds_read_b128 v[184:187], v144 offset:49152
	ds_read_b128 v[188:191], v144 offset:50176
	ds_read_b128 v[192:195], v144 offset:51200
	ds_read_b128 v[204:207], v144 offset:52224
	ds_read_b128 v[212:215], v144 offset:53248
	ds_read_b128 v[216:219], v144 offset:54272
	ds_read_b128 v[220:223], v144 offset:55296
	ds_read_b128 v[232:235], v144 offset:56320
	global_load_lds_dwordx4 v[236:237], off
	s_add_i32 m0, s31, 0x2000
	s_add_u32 s34, s50, 0x40080
	v_lshl_add_u64 v[236:237], v[238:239], 0, s[10:11]
	s_addc_u32 s35, s51, 0
	s_add_i32 s31, s36, s1
	global_load_lds_dwordx4 v[236:237], off
	v_lshl_add_u64 v[236:237], s[34:35], 0, v[196:197]
	s_mov_b32 m0, s31
	s_nop 0
	global_load_lds_dwordx4 v[236:237], off
	v_lshl_add_u64 v[236:237], s[34:35], 0, v[132:133]
	s_add_i32 m0, s31, 0x2000
	s_nop 0
	global_load_lds_dwordx4 v[236:237], off
	v_lshl_add_u64 v[236:237], v[240:241], 0, s[10:11]
	s_mov_b32 m0, s22
	s_nop 0
	global_load_lds_dwordx4 v[236:237], off
	v_lshl_add_u64 v[236:237], v[242:243], 0, s[10:11]
	s_mov_b32 m0, s23
	s_nop 0
	global_load_lds_dwordx4 v[236:237], off
	s_waitcnt vmcnt(8)
	s_waitcnt lgkmcnt(0)
	s_barrier
	s_waitcnt lgkmcnt(0)
	v_mfma_f32_16x16x32_bf16 v[60:63], v[146:149], v[184:187], v[60:63]
	v_mfma_f32_16x16x32_bf16 v[56:59], v[156:159], v[184:187], v[56:59]
	v_mfma_f32_16x16x32_bf16 v[44:47], v[146:149], v[192:195], v[44:47]
	v_mfma_f32_16x16x32_bf16 v[40:43], v[156:159], v[192:195], v[40:43]
	v_mfma_f32_16x16x32_bf16 v[28:31], v[146:149], v[212:215], v[28:31]
	v_mfma_f32_16x16x32_bf16 v[24:27], v[156:159], v[212:215], v[24:27]
	v_mfma_f32_16x16x32_bf16 v[12:15], v[146:149], v[220:223], v[12:15]
	v_mfma_f32_16x16x32_bf16 v[8:11], v[156:159], v[220:223], v[8:11]
	v_mfma_f32_16x16x32_bf16 v[60:63], v[150:153], v[188:191], v[60:63]
	v_mfma_f32_16x16x32_bf16 v[56:59], v[164:167], v[188:191], v[56:59]
	v_mfma_f32_16x16x32_bf16 v[44:47], v[150:153], v[204:207], v[44:47]
	v_mfma_f32_16x16x32_bf16 v[40:43], v[164:167], v[204:207], v[40:43]
	v_mfma_f32_16x16x32_bf16 v[28:31], v[150:153], v[216:219], v[28:31]
	v_mfma_f32_16x16x32_bf16 v[24:27], v[164:167], v[216:219], v[24:27]
	v_mfma_f32_16x16x32_bf16 v[12:15], v[150:153], v[232:235], v[12:15]
	v_mfma_f32_16x16x32_bf16 v[8:11], v[164:167], v[232:235], v[8:11]
	v_mfma_f32_16x16x32_bf16 v[52:55], v[168:171], v[184:187], v[52:55]
	v_mfma_f32_16x16x32_bf16 v[48:51], v[176:179], v[184:187], v[48:51]
	v_mfma_f32_16x16x32_bf16 v[36:39], v[168:171], v[192:195], v[36:39]
	v_mfma_f32_16x16x32_bf16 v[32:35], v[176:179], v[192:195], v[32:35]
	v_mfma_f32_16x16x32_bf16 v[20:23], v[168:171], v[212:215], v[20:23]
	v_mfma_f32_16x16x32_bf16 v[16:19], v[176:179], v[212:215], v[16:19]
	v_mfma_f32_16x16x32_bf16 v[4:7], v[168:171], v[220:223], v[4:7]
	v_mfma_f32_16x16x32_bf16 v[0:3], v[176:179], v[220:223], v[0:3]
	v_mfma_f32_16x16x32_bf16 v[52:55], v[172:175], v[188:191], v[52:55]
	v_mfma_f32_16x16x32_bf16 v[48:51], v[180:183], v[188:191], v[48:51]
	v_mfma_f32_16x16x32_bf16 v[36:39], v[172:175], v[204:207], v[36:39]
	v_mfma_f32_16x16x32_bf16 v[32:35], v[180:183], v[204:207], v[32:35]
	v_mfma_f32_16x16x32_bf16 v[20:23], v[172:175], v[216:219], v[20:23]
	v_mfma_f32_16x16x32_bf16 v[16:19], v[180:183], v[216:219], v[16:19]
	v_mfma_f32_16x16x32_bf16 v[4:7], v[172:175], v[232:235], v[4:7]
	v_mfma_f32_16x16x32_bf16 v[0:3], v[180:183], v[232:235], v[0:3]
	s_barrier
	s_add_i32 s30, s30, 2
	s_add_u32 s48, s48, 0x100
	s_addc_u32 s49, s49, 0
	s_cmp_gt_u32 s30, 13
	s_cbranch_scc0 .LBB0_978
	s_add_u32 s48, s26, 0xffffff00
	s_addc_u32 s49, s27, -1
	s_andn2_b64 vcc, exec, s[40:41]
	s_cbranch_vccnz .LBB0_981
	v_mov_b32_e32 v0, 0
	s_mov_b32 s42, s8
	s_mov_b32 s18, s12
	s_mov_b64 s[6:7], s[46:47]
	s_mov_b32 s24, s25
	v_mov_b32_e32 v1, v0
	v_mov_b32_e32 v2, v0
	v_mov_b32_e32 v3, v0
	v_mov_b32_e32 v4, v0
	v_mov_b32_e32 v5, v0
	v_mov_b32_e32 v6, v0
	v_mov_b32_e32 v7, v0
	v_mov_b32_e32 v16, v0
	v_mov_b32_e32 v17, v0
	v_mov_b32_e32 v18, v0
	v_mov_b32_e32 v19, v0
	v_mov_b32_e32 v20, v0
	v_mov_b32_e32 v21, v0
	v_mov_b32_e32 v22, v0
	v_mov_b32_e32 v23, v0
	v_mov_b32_e32 v32, v0
	v_mov_b32_e32 v33, v0
	v_mov_b32_e32 v34, v0
	v_mov_b32_e32 v35, v0
	v_mov_b32_e32 v36, v0
	v_mov_b32_e32 v37, v0
	v_mov_b32_e32 v38, v0
	v_mov_b32_e32 v39, v0
	v_mov_b32_e32 v48, v0
	v_mov_b32_e32 v49, v0
	v_mov_b32_e32 v50, v0
	v_mov_b32_e32 v51, v0
	v_mov_b32_e32 v52, v0
	v_mov_b32_e32 v53, v0
	v_mov_b32_e32 v54, v0
	v_mov_b32_e32 v55, v0
	v_mov_b32_e32 v8, v0
	v_mov_b32_e32 v9, v0
	v_mov_b32_e32 v10, v0
	v_mov_b32_e32 v11, v0
	v_mov_b32_e32 v12, v0
	v_mov_b32_e32 v13, v0
	v_mov_b32_e32 v14, v0
	v_mov_b32_e32 v15, v0
	v_mov_b32_e32 v24, v0
	v_mov_b32_e32 v25, v0
	v_mov_b32_e32 v26, v0
	v_mov_b32_e32 v27, v0
	v_mov_b32_e32 v28, v0
	v_mov_b32_e32 v29, v0
	v_mov_b32_e32 v30, v0
	v_mov_b32_e32 v31, v0
	v_mov_b32_e32 v40, v0
	v_mov_b32_e32 v41, v0
	v_mov_b32_e32 v42, v0
	v_mov_b32_e32 v43, v0
	v_mov_b32_e32 v44, v0
	v_mov_b32_e32 v45, v0
	v_mov_b32_e32 v46, v0
	v_mov_b32_e32 v47, v0
	v_mov_b32_e32 v56, v0
	v_mov_b32_e32 v57, v0
	v_mov_b32_e32 v58, v0
	v_mov_b32_e32 v59, v0
	v_mov_b32_e32 v60, v0
	v_mov_b32_e32 v61, v0
	v_mov_b32_e32 v62, v0
	v_mov_b32_e32 v63, v0
	v_mov_b32_e32 v64, v0
	v_mov_b32_e32 v65, v0
	v_mov_b32_e32 v66, v0
	v_mov_b32_e32 v67, v0
	v_mov_b32_e32 v68, v0
	v_mov_b32_e32 v69, v0
	v_mov_b32_e32 v70, v0
	v_mov_b32_e32 v71, v0
	v_mov_b32_e32 v80, v0
	v_mov_b32_e32 v81, v0
	v_mov_b32_e32 v82, v0
	v_mov_b32_e32 v83, v0
	v_mov_b32_e32 v84, v0
	v_mov_b32_e32 v85, v0
	v_mov_b32_e32 v86, v0
	v_mov_b32_e32 v87, v0
	v_mov_b32_e32 v96, v0
	v_mov_b32_e32 v97, v0
	v_mov_b32_e32 v98, v0
	v_mov_b32_e32 v99, v0
	v_mov_b32_e32 v100, v0
	v_mov_b32_e32 v101, v0
	v_mov_b32_e32 v102, v0
	v_mov_b32_e32 v103, v0
	v_mov_b32_e32 v112, v0
	v_mov_b32_e32 v113, v0
	v_mov_b32_e32 v114, v0
	v_mov_b32_e32 v115, v0
	v_mov_b32_e32 v116, v0
	v_mov_b32_e32 v117, v0
	v_mov_b32_e32 v118, v0
	v_mov_b32_e32 v119, v0
	v_mov_b32_e32 v72, v0
	v_mov_b32_e32 v73, v0
	v_mov_b32_e32 v74, v0
	v_mov_b32_e32 v75, v0
	v_mov_b32_e32 v76, v0
	v_mov_b32_e32 v77, v0
	v_mov_b32_e32 v78, v0
	v_mov_b32_e32 v79, v0
	v_mov_b32_e32 v88, v0
	v_mov_b32_e32 v89, v0
	v_mov_b32_e32 v90, v0
	v_mov_b32_e32 v91, v0
	v_mov_b32_e32 v92, v0
	v_mov_b32_e32 v93, v0
	v_mov_b32_e32 v94, v0
	v_mov_b32_e32 v95, v0
	v_mov_b32_e32 v104, v0
	v_mov_b32_e32 v105, v0
	v_mov_b32_e32 v106, v0
	v_mov_b32_e32 v107, v0
	v_mov_b32_e32 v108, v0
	v_mov_b32_e32 v109, v0
	v_mov_b32_e32 v110, v0
	v_mov_b32_e32 v111, v0
	v_mov_b32_e32 v120, v0
	v_mov_b32_e32 v121, v0
	v_mov_b32_e32 v122, v0
	v_mov_b32_e32 v123, v0
	v_mov_b32_e32 v124, v0
	v_mov_b32_e32 v125, v0
	v_mov_b32_e32 v126, v0
	v_mov_b32_e32 v127, v0
	s_branch .LBB0_982

.LBB0_1033:
	s_add_u32 s35, s12, s48
	s_addc_u32 s36, s13, s49
	s_add_u32 s35, s35, 0x100
	s_addc_u32 s36, s36, 0
	s_add_u32 s37, s27, s48
	s_addc_u32 s43, s28, s49
	s_add_i32 s58, 0, 0x10000
	s_cmpk_eq_i32 s48, 0x700
	s_cselect_b32 s53, s29, s36
	s_cselect_b32 s52, s30, s35
	v_add_u32_e32 v147, s58, v144
	s_cselect_b32 s51, s19, s43
	s_cselect_b32 s50, s31, s37
	s_add_i32 s35, 0, 0x14000
	ds_read_b128 v[148:151], v147
	ds_read_b128 v[152:155], v147 offset:1024
	ds_read_b128 v[156:159], v147 offset:2048
	ds_read_b128 v[164:167], v147 offset:3072
	v_add_u32_e32 v147, s35, v144
	ds_read_b128 v[168:171], v147
	ds_read_b128 v[172:175], v147 offset:1024
	ds_read_b128 v[176:179], v147 offset:2048
	ds_read_b128 v[180:183], v147 offset:3072
	v_lshl_add_u64 v[236:237], v[138:139], 0, s[48:49]
	s_add_i32 m0, s7, 0xc000
	ds_read_b128 v[184:187], v145
	ds_read_b128 v[188:191], v145 offset:1024
	ds_read_b128 v[192:195], v145 offset:2048
	ds_read_b128 v[204:207], v145 offset:3072
	ds_read_b128 v[212:215], v145 offset:4096
	ds_read_b128 v[216:219], v145 offset:5120
	ds_read_b128 v[220:223], v145 offset:6144
	ds_read_b128 v[232:235], v145 offset:7168
	global_load_lds_dwordx4 v[236:237], off
	v_lshl_add_u64 v[236:237], v[140:141], 0, s[48:49]
	s_add_i32 m0, s7, 0xe000
	s_nop 0
	global_load_lds_dwordx4 v[236:237], off
	s_waitcnt vmcnt(8)
	s_waitcnt lgkmcnt(0)
	s_barrier
	s_waitcnt lgkmcnt(0)
	v_mfma_f32_16x16x32_bf16 v[76:79], v[148:151], v[184:187], v[76:79]
	v_mfma_f32_16x16x32_bf16 v[72:75], v[156:159], v[184:187], v[72:75]
	v_mfma_f32_16x16x32_bf16 v[116:119], v[148:151], v[192:195], v[116:119]
	v_mfma_f32_16x16x32_bf16 v[112:115], v[156:159], v[192:195], v[112:115]
	v_mfma_f32_16x16x32_bf16 v[88:91], v[148:151], v[212:215], v[88:91]
	v_mfma_f32_16x16x32_bf16 v[84:87], v[156:159], v[212:215], v[84:87]
	v_mfma_f32_16x16x32_bf16 v[108:111], v[148:151], v[220:223], v[108:111]
	v_mfma_f32_16x16x32_bf16 v[104:107], v[156:159], v[220:223], v[104:107]
	v_mfma_f32_16x16x32_bf16 v[76:79], v[152:155], v[188:191], v[76:79]
	v_mfma_f32_16x16x32_bf16 v[72:75], v[164:167], v[188:191], v[72:75]
	v_mfma_f32_16x16x32_bf16 v[116:119], v[152:155], v[204:207], v[116:119]
	v_mfma_f32_16x16x32_bf16 v[112:115], v[164:167], v[204:207], v[112:115]
	v_mfma_f32_16x16x32_bf16 v[88:91], v[152:155], v[216:219], v[88:91]
	v_mfma_f32_16x16x32_bf16 v[84:87], v[164:167], v[216:219], v[84:87]
	v_mfma_f32_16x16x32_bf16 v[108:111], v[152:155], v[232:235], v[108:111]
	v_mfma_f32_16x16x32_bf16 v[104:107], v[164:167], v[232:235], v[104:107]
	v_mfma_f32_16x16x32_bf16 v[96:99], v[168:171], v[184:187], v[96:99]
	v_mfma_f32_16x16x32_bf16 v[92:95], v[176:179], v[184:187], v[92:95]
	v_mfma_f32_16x16x32_bf16 v[124:127], v[168:171], v[192:195], v[124:127]
	v_mfma_f32_16x16x32_bf16 v[120:123], v[176:179], v[192:195], v[120:123]
	v_mfma_f32_16x16x32_bf16 v[100:103], v[168:171], v[212:215], v[100:103]
	v_mfma_f32_16x16x32_bf16 v[80:83], v[176:179], v[212:215], v[80:83]
	v_mfma_f32_16x16x32_bf16 v[68:71], v[168:171], v[220:223], v[68:71]
	v_mfma_f32_16x16x32_bf16 v[64:67], v[176:179], v[220:223], v[64:67]
	v_mfma_f32_16x16x32_bf16 v[96:99], v[172:175], v[188:191], v[96:99]
	v_mfma_f32_16x16x32_bf16 v[92:95], v[180:183], v[188:191], v[92:95]
	v_mfma_f32_16x16x32_bf16 v[124:127], v[172:175], v[204:207], v[124:127]
	v_mfma_f32_16x16x32_bf16 v[120:123], v[180:183], v[204:207], v[120:123]
	v_mfma_f32_16x16x32_bf16 v[100:103], v[172:175], v[216:219], v[100:103]
	v_mfma_f32_16x16x32_bf16 v[80:83], v[180:183], v[216:219], v[80:83]
	v_mfma_f32_16x16x32_bf16 v[68:71], v[172:175], v[232:235], v[68:71]
	v_mfma_f32_16x16x32_bf16 v[64:67], v[180:183], v[232:235], v[64:67]
	s_barrier
	s_add_i32 s36, s58, s9
	v_lshl_add_u64 v[236:237], s[50:51], 0, v[196:197]
	s_mov_b32 m0, s36
	ds_read_b128 v[184:187], v145 offset:16384
	ds_read_b128 v[188:191], v145 offset:17408
	ds_read_b128 v[192:195], v145 offset:18432
	ds_read_b128 v[204:207], v145 offset:19456
	ds_read_b128 v[212:215], v145 offset:20480
	ds_read_b128 v[216:219], v145 offset:21504
	ds_read_b128 v[220:223], v145 offset:22528
	ds_read_b128 v[232:235], v145 offset:23552
	global_load_lds_dwordx4 v[236:237], off
	s_add_i32 m0, s36, 0x2000
	s_add_u32 s36, s50, 0x40000
	v_lshl_add_u64 v[238:239], s[50:51], 0, v[132:133]
	s_addc_u32 s37, s51, 0
	s_add_i32 s35, s35, s9
	global_load_lds_dwordx4 v[238:239], off
	v_lshl_add_u64 v[240:241], s[36:37], 0, v[196:197]
	s_mov_b32 m0, s35
	v_lshl_add_u64 v[242:243], s[52:53], 0, v[130:131]
	global_load_lds_dwordx4 v[240:241], off
	v_lshl_add_u64 v[240:241], s[36:37], 0, v[132:133]
	s_add_i32 m0, s35, 0x2000
	s_nop 0
	global_load_lds_dwordx4 v[240:241], off
	v_lshl_add_u64 v[240:241], s[52:53], 0, v[128:129]
	s_mov_b32 m0, s7
	s_nop 0
	global_load_lds_dwordx4 v[240:241], off
	s_mov_b32 m0, s20
	s_nop 0
	global_load_lds_dwordx4 v[242:243], off
	s_waitcnt vmcnt(8)
	s_waitcnt lgkmcnt(0)
	s_barrier
	s_waitcnt lgkmcnt(0)
	v_mfma_f32_16x16x32_bf16 v[60:63], v[148:151], v[184:187], v[60:63]
	v_mfma_f32_16x16x32_bf16 v[56:59], v[156:159], v[184:187], v[56:59]
	v_mfma_f32_16x16x32_bf16 v[44:47], v[148:151], v[192:195], v[44:47]
	v_mfma_f32_16x16x32_bf16 v[40:43], v[156:159], v[192:195], v[40:43]
	v_mfma_f32_16x16x32_bf16 v[28:31], v[148:151], v[212:215], v[28:31]
	v_mfma_f32_16x16x32_bf16 v[24:27], v[156:159], v[212:215], v[24:27]
	v_mfma_f32_16x16x32_bf16 v[12:15], v[148:151], v[220:223], v[12:15]
	v_mfma_f32_16x16x32_bf16 v[8:11], v[156:159], v[220:223], v[8:11]
	v_mfma_f32_16x16x32_bf16 v[60:63], v[152:155], v[188:191], v[60:63]
	v_mfma_f32_16x16x32_bf16 v[56:59], v[164:167], v[188:191], v[56:59]
	v_mfma_f32_16x16x32_bf16 v[44:47], v[152:155], v[204:207], v[44:47]
	v_mfma_f32_16x16x32_bf16 v[40:43], v[164:167], v[204:207], v[40:43]
	v_mfma_f32_16x16x32_bf16 v[28:31], v[152:155], v[216:219], v[28:31]
	v_mfma_f32_16x16x32_bf16 v[24:27], v[164:167], v[216:219], v[24:27]
	v_mfma_f32_16x16x32_bf16 v[12:15], v[152:155], v[232:235], v[12:15]
	v_mfma_f32_16x16x32_bf16 v[8:11], v[164:167], v[232:235], v[8:11]
	v_mfma_f32_16x16x32_bf16 v[52:55], v[168:171], v[184:187], v[52:55]
	v_mfma_f32_16x16x32_bf16 v[48:51], v[176:179], v[184:187], v[48:51]
	v_mfma_f32_16x16x32_bf16 v[36:39], v[168:171], v[192:195], v[36:39]
	v_mfma_f32_16x16x32_bf16 v[32:35], v[176:179], v[192:195], v[32:35]
	v_mfma_f32_16x16x32_bf16 v[20:23], v[168:171], v[212:215], v[20:23]
	v_mfma_f32_16x16x32_bf16 v[16:19], v[176:179], v[212:215], v[16:19]
	v_mfma_f32_16x16x32_bf16 v[4:7], v[168:171], v[220:223], v[4:7]
	v_mfma_f32_16x16x32_bf16 v[0:3], v[176:179], v[220:223], v[0:3]
	v_mfma_f32_16x16x32_bf16 v[52:55], v[172:175], v[188:191], v[52:55]
	v_mfma_f32_16x16x32_bf16 v[48:51], v[180:183], v[188:191], v[48:51]
	v_mfma_f32_16x16x32_bf16 v[36:39], v[172:175], v[204:207], v[36:39]
	v_mfma_f32_16x16x32_bf16 v[32:35], v[180:183], v[204:207], v[32:35]
	v_mfma_f32_16x16x32_bf16 v[20:23], v[172:175], v[216:219], v[20:23]
	v_mfma_f32_16x16x32_bf16 v[16:19], v[180:183], v[216:219], v[16:19]
	v_mfma_f32_16x16x32_bf16 v[4:7], v[172:175], v[232:235], v[4:7]
	v_mfma_f32_16x16x32_bf16 v[0:3], v[180:183], v[232:235], v[0:3]
	s_barrier
	s_add_i32 s35, 0, 0x18000
	v_add_u32_e32 v147, s35, v144
	s_add_i32 s43, 0, 0x1c000
	ds_read_b128 v[148:151], v147
	ds_read_b128 v[152:155], v147 offset:1024
	ds_read_b128 v[156:159], v147 offset:2048
	ds_read_b128 v[164:167], v147 offset:3072
	v_add_u32_e32 v147, s43, v144
	ds_read_b128 v[168:171], v147
	ds_read_b128 v[172:175], v147 offset:1024
	ds_read_b128 v[176:179], v147 offset:2048
	ds_read_b128 v[180:183], v147 offset:3072
	s_add_u32 s36, s52, 0x40000
	s_addc_u32 s37, s53, 0
	s_mov_b32 m0, s21
	v_lshl_add_u64 v[244:245], s[36:37], 0, v[128:129]
	ds_read_b128 v[184:187], v145 offset:32768
	ds_read_b128 v[188:191], v145 offset:33792
	ds_read_b128 v[192:195], v145 offset:34816
	ds_read_b128 v[204:207], v145 offset:35840
	ds_read_b128 v[212:215], v145 offset:36864
	ds_read_b128 v[216:219], v145 offset:37888
	ds_read_b128 v[220:223], v145 offset:38912
	ds_read_b128 v[232:235], v145 offset:39936
	global_load_lds_dwordx4 v[244:245], off
	v_lshl_add_u64 v[244:245], s[36:37], 0, v[130:131]
	s_mov_b32 m0, s22
	s_nop 0
	global_load_lds_dwordx4 v[244:245], off
	s_waitcnt vmcnt(8)
	s_waitcnt lgkmcnt(0)
	s_barrier
	s_waitcnt lgkmcnt(0)
	v_mfma_f32_16x16x32_bf16 v[76:79], v[148:151], v[184:187], v[76:79]
	v_mfma_f32_16x16x32_bf16 v[72:75], v[156:159], v[184:187], v[72:75]
	v_mfma_f32_16x16x32_bf16 v[116:119], v[148:151], v[192:195], v[116:119]
	v_mfma_f32_16x16x32_bf16 v[112:115], v[156:159], v[192:195], v[112:115]
	v_mfma_f32_16x16x32_bf16 v[88:91], v[148:151], v[212:215], v[88:91]
	v_mfma_f32_16x16x32_bf16 v[84:87], v[156:159], v[212:215], v[84:87]
	v_mfma_f32_16x16x32_bf16 v[108:111], v[148:151], v[220:223], v[108:111]
	v_mfma_f32_16x16x32_bf16 v[104:107], v[156:159], v[220:223], v[104:107]
	v_mfma_f32_16x16x32_bf16 v[76:79], v[152:155], v[188:191], v[76:79]
	v_mfma_f32_16x16x32_bf16 v[72:75], v[164:167], v[188:191], v[72:75]
	v_mfma_f32_16x16x32_bf16 v[116:119], v[152:155], v[204:207], v[116:119]
	v_mfma_f32_16x16x32_bf16 v[112:115], v[164:167], v[204:207], v[112:115]
	v_mfma_f32_16x16x32_bf16 v[88:91], v[152:155], v[216:219], v[88:91]
	v_mfma_f32_16x16x32_bf16 v[84:87], v[164:167], v[216:219], v[84:87]
	v_mfma_f32_16x16x32_bf16 v[108:111], v[152:155], v[232:235], v[108:111]
	v_mfma_f32_16x16x32_bf16 v[104:107], v[164:167], v[232:235], v[104:107]
	v_mfma_f32_16x16x32_bf16 v[96:99], v[168:171], v[184:187], v[96:99]
	v_mfma_f32_16x16x32_bf16 v[92:95], v[176:179], v[184:187], v[92:95]
	v_mfma_f32_16x16x32_bf16 v[124:127], v[168:171], v[192:195], v[124:127]
	v_mfma_f32_16x16x32_bf16 v[120:123], v[176:179], v[192:195], v[120:123]
	v_mfma_f32_16x16x32_bf16 v[100:103], v[168:171], v[212:215], v[100:103]
	v_mfma_f32_16x16x32_bf16 v[80:83], v[176:179], v[212:215], v[80:83]
	v_mfma_f32_16x16x32_bf16 v[68:71], v[168:171], v[220:223], v[68:71]
	v_mfma_f32_16x16x32_bf16 v[64:67], v[176:179], v[220:223], v[64:67]
	v_mfma_f32_16x16x32_bf16 v[96:99], v[172:175], v[188:191], v[96:99]
	v_mfma_f32_16x16x32_bf16 v[92:95], v[180:183], v[188:191], v[92:95]
	v_mfma_f32_16x16x32_bf16 v[124:127], v[172:175], v[204:207], v[124:127]
	v_mfma_f32_16x16x32_bf16 v[120:123], v[180:183], v[204:207], v[120:123]
	v_mfma_f32_16x16x32_bf16 v[100:103], v[172:175], v[216:219], v[100:103]
	v_mfma_f32_16x16x32_bf16 v[80:83], v[180:183], v[216:219], v[80:83]
	v_mfma_f32_16x16x32_bf16 v[68:71], v[172:175], v[232:235], v[68:71]
	v_mfma_f32_16x16x32_bf16 v[64:67], v[180:183], v[232:235], v[64:67]
	s_barrier
	s_add_i32 s35, s35, s9
	v_lshl_add_u64 v[236:237], v[236:237], 0, s[10:11]
	s_mov_b32 m0, s35
	ds_read_b128 v[184:187], v145 offset:49152
	ds_read_b128 v[188:191], v145 offset:50176
	ds_read_b128 v[192:195], v145 offset:51200
	ds_read_b128 v[204:207], v145 offset:52224
	ds_read_b128 v[212:215], v145 offset:53248
	ds_read_b128 v[216:219], v145 offset:54272
	ds_read_b128 v[220:223], v145 offset:55296
	ds_read_b128 v[232:235], v145 offset:56320
	global_load_lds_dwordx4 v[236:237], off
	s_add_i32 m0, s35, 0x2000
	s_add_u32 s36, s50, 0x40080
	v_lshl_add_u64 v[236:237], v[238:239], 0, s[10:11]
	s_addc_u32 s37, s51, 0
	s_add_i32 s35, s43, s9
	global_load_lds_dwordx4 v[236:237], off
	v_lshl_add_u64 v[236:237], s[36:37], 0, v[196:197]
	s_mov_b32 m0, s35
	s_nop 0
	global_load_lds_dwordx4 v[236:237], off
	v_lshl_add_u64 v[236:237], s[36:37], 0, v[132:133]
	s_add_i32 m0, s35, 0x2000
	s_nop 0
	global_load_lds_dwordx4 v[236:237], off
	v_lshl_add_u64 v[236:237], v[240:241], 0, s[10:11]
	s_mov_b32 m0, s23
	s_nop 0
	global_load_lds_dwordx4 v[236:237], off
	v_lshl_add_u64 v[236:237], v[242:243], 0, s[10:11]
	s_mov_b32 m0, s24
	s_nop 0
	global_load_lds_dwordx4 v[236:237], off
	s_waitcnt vmcnt(8)
	s_waitcnt lgkmcnt(0)
	s_barrier
	s_waitcnt lgkmcnt(0)
	v_mfma_f32_16x16x32_bf16 v[60:63], v[148:151], v[184:187], v[60:63]
	v_mfma_f32_16x16x32_bf16 v[56:59], v[156:159], v[184:187], v[56:59]
	v_mfma_f32_16x16x32_bf16 v[44:47], v[148:151], v[192:195], v[44:47]
	v_mfma_f32_16x16x32_bf16 v[40:43], v[156:159], v[192:195], v[40:43]
	v_mfma_f32_16x16x32_bf16 v[28:31], v[148:151], v[212:215], v[28:31]
	v_mfma_f32_16x16x32_bf16 v[24:27], v[156:159], v[212:215], v[24:27]
	v_mfma_f32_16x16x32_bf16 v[12:15], v[148:151], v[220:223], v[12:15]
	v_mfma_f32_16x16x32_bf16 v[8:11], v[156:159], v[220:223], v[8:11]
	v_mfma_f32_16x16x32_bf16 v[60:63], v[152:155], v[188:191], v[60:63]
	v_mfma_f32_16x16x32_bf16 v[56:59], v[164:167], v[188:191], v[56:59]
	v_mfma_f32_16x16x32_bf16 v[44:47], v[152:155], v[204:207], v[44:47]
	v_mfma_f32_16x16x32_bf16 v[40:43], v[164:167], v[204:207], v[40:43]
	v_mfma_f32_16x16x32_bf16 v[28:31], v[152:155], v[216:219], v[28:31]
	v_mfma_f32_16x16x32_bf16 v[24:27], v[164:167], v[216:219], v[24:27]
	v_mfma_f32_16x16x32_bf16 v[12:15], v[152:155], v[232:235], v[12:15]
	v_mfma_f32_16x16x32_bf16 v[8:11], v[164:167], v[232:235], v[8:11]
	v_mfma_f32_16x16x32_bf16 v[52:55], v[168:171], v[184:187], v[52:55]
	v_mfma_f32_16x16x32_bf16 v[48:51], v[176:179], v[184:187], v[48:51]
	v_mfma_f32_16x16x32_bf16 v[36:39], v[168:171], v[192:195], v[36:39]
	v_mfma_f32_16x16x32_bf16 v[32:35], v[176:179], v[192:195], v[32:35]
	v_mfma_f32_16x16x32_bf16 v[20:23], v[168:171], v[212:215], v[20:23]
	v_mfma_f32_16x16x32_bf16 v[16:19], v[176:179], v[212:215], v[16:19]
	v_mfma_f32_16x16x32_bf16 v[4:7], v[168:171], v[220:223], v[4:7]
	v_mfma_f32_16x16x32_bf16 v[0:3], v[176:179], v[220:223], v[0:3]
	v_mfma_f32_16x16x32_bf16 v[52:55], v[172:175], v[188:191], v[52:55]
	v_mfma_f32_16x16x32_bf16 v[48:51], v[180:183], v[188:191], v[48:51]
	v_mfma_f32_16x16x32_bf16 v[36:39], v[172:175], v[204:207], v[36:39]
	v_mfma_f32_16x16x32_bf16 v[32:35], v[180:183], v[204:207], v[32:35]
	v_mfma_f32_16x16x32_bf16 v[20:23], v[172:175], v[216:219], v[20:23]
	v_mfma_f32_16x16x32_bf16 v[16:19], v[180:183], v[216:219], v[16:19]
	v_mfma_f32_16x16x32_bf16 v[4:7], v[172:175], v[232:235], v[4:7]
	v_mfma_f32_16x16x32_bf16 v[0:3], v[180:183], v[232:235], v[0:3]
	s_barrier
	s_add_i32 s34, s34, 2
	s_add_u32 s48, s48, 0x100
	s_addc_u32 s49, s49, 0
	s_cmp_gt_u32 s34, 13
	s_cbranch_scc0 .LBB0_1033
	s_add_u32 s48, s27, 0xffffff00
	s_addc_u32 s49, s28, -1
	s_andn2_b64 vcc, exec, s[40:41]
	s_cbranch_vccnz .LBB0_1036
	v_mov_b32_e32 v0, 0
	s_mov_b32 s8, s18
	s_mov_b32 s6, s42
	s_mov_b64 s[12:13], s[46:47]
	s_mov_b32 s25, s26
	v_mov_b32_e32 v1, v0
	v_mov_b32_e32 v2, v0
	v_mov_b32_e32 v3, v0
	v_mov_b32_e32 v4, v0
	v_mov_b32_e32 v5, v0
	v_mov_b32_e32 v6, v0
	v_mov_b32_e32 v7, v0
	v_mov_b32_e32 v16, v0
	v_mov_b32_e32 v17, v0
	v_mov_b32_e32 v18, v0
	v_mov_b32_e32 v19, v0
	v_mov_b32_e32 v20, v0
	v_mov_b32_e32 v21, v0
	v_mov_b32_e32 v22, v0
	v_mov_b32_e32 v23, v0
	v_mov_b32_e32 v32, v0
	v_mov_b32_e32 v33, v0
	v_mov_b32_e32 v34, v0
	v_mov_b32_e32 v35, v0
	v_mov_b32_e32 v36, v0
	v_mov_b32_e32 v37, v0
	v_mov_b32_e32 v38, v0
	v_mov_b32_e32 v39, v0
	v_mov_b32_e32 v48, v0
	v_mov_b32_e32 v49, v0
	v_mov_b32_e32 v50, v0
	v_mov_b32_e32 v51, v0
	v_mov_b32_e32 v52, v0
	v_mov_b32_e32 v53, v0
	v_mov_b32_e32 v54, v0
	v_mov_b32_e32 v55, v0
	v_mov_b32_e32 v8, v0
	v_mov_b32_e32 v9, v0
	v_mov_b32_e32 v10, v0
	v_mov_b32_e32 v11, v0
	v_mov_b32_e32 v12, v0
	v_mov_b32_e32 v13, v0
	v_mov_b32_e32 v14, v0
	v_mov_b32_e32 v15, v0
	v_mov_b32_e32 v24, v0
	v_mov_b32_e32 v25, v0
	v_mov_b32_e32 v26, v0
	v_mov_b32_e32 v27, v0
	v_mov_b32_e32 v28, v0
	v_mov_b32_e32 v29, v0
	v_mov_b32_e32 v30, v0
	v_mov_b32_e32 v31, v0
	v_mov_b32_e32 v40, v0
	v_mov_b32_e32 v41, v0
	v_mov_b32_e32 v42, v0
	v_mov_b32_e32 v43, v0
	v_mov_b32_e32 v44, v0
	v_mov_b32_e32 v45, v0
	v_mov_b32_e32 v46, v0
	v_mov_b32_e32 v47, v0
	v_mov_b32_e32 v56, v0
	v_mov_b32_e32 v57, v0
	v_mov_b32_e32 v58, v0
	v_mov_b32_e32 v59, v0
	v_mov_b32_e32 v60, v0
	v_mov_b32_e32 v61, v0
	v_mov_b32_e32 v62, v0
	v_mov_b32_e32 v63, v0
	v_mov_b32_e32 v64, v0
	v_mov_b32_e32 v65, v0
	v_mov_b32_e32 v66, v0
	v_mov_b32_e32 v67, v0
	v_mov_b32_e32 v68, v0
	v_mov_b32_e32 v69, v0
	v_mov_b32_e32 v70, v0
	v_mov_b32_e32 v71, v0
	v_mov_b32_e32 v80, v0
	v_mov_b32_e32 v81, v0
	v_mov_b32_e32 v82, v0
	v_mov_b32_e32 v83, v0
	v_mov_b32_e32 v100, v0
	v_mov_b32_e32 v101, v0
	v_mov_b32_e32 v102, v0
	v_mov_b32_e32 v103, v0
	v_mov_b32_e32 v120, v0
	v_mov_b32_e32 v121, v0
	v_mov_b32_e32 v122, v0
	v_mov_b32_e32 v123, v0
	v_mov_b32_e32 v124, v0
	v_mov_b32_e32 v125, v0
	v_mov_b32_e32 v126, v0
	v_mov_b32_e32 v127, v0
	v_mov_b32_e32 v92, v0
	v_mov_b32_e32 v93, v0
	v_mov_b32_e32 v94, v0
	v_mov_b32_e32 v95, v0
	v_mov_b32_e32 v96, v0
	v_mov_b32_e32 v97, v0
	v_mov_b32_e32 v98, v0
	v_mov_b32_e32 v99, v0
	v_mov_b32_e32 v104, v0
	v_mov_b32_e32 v105, v0
	v_mov_b32_e32 v106, v0
	v_mov_b32_e32 v107, v0
	v_mov_b32_e32 v108, v0
	v_mov_b32_e32 v109, v0
	v_mov_b32_e32 v110, v0
	v_mov_b32_e32 v111, v0
	v_mov_b32_e32 v84, v0
	v_mov_b32_e32 v85, v0
	v_mov_b32_e32 v86, v0
	v_mov_b32_e32 v87, v0
	v_mov_b32_e32 v88, v0
	v_mov_b32_e32 v89, v0
	v_mov_b32_e32 v90, v0
	v_mov_b32_e32 v91, v0
	v_mov_b32_e32 v112, v0
	v_mov_b32_e32 v113, v0
	v_mov_b32_e32 v114, v0
	v_mov_b32_e32 v115, v0
	v_mov_b32_e32 v116, v0
	v_mov_b32_e32 v117, v0
	v_mov_b32_e32 v118, v0
	v_mov_b32_e32 v119, v0
	v_mov_b32_e32 v72, v0
	v_mov_b32_e32 v73, v0
	v_mov_b32_e32 v74, v0
	v_mov_b32_e32 v75, v0
	v_mov_b32_e32 v76, v0
	v_mov_b32_e32 v77, v0
	v_mov_b32_e32 v78, v0
	v_mov_b32_e32 v79, v0
	s_branch .LBB0_1037
